# masked attention steps select -inf with v_bfe_i32+v_bfi_b32 (2 VALU per score instead of 3)
# speedup vs baseline: 1.0409x; 1.0029x over previous
; DI float fexp2(float x) { return __builtin_amdgcn_exp2f(x); }
; DI f32x16 mfma32(bf16x8 a, bf16x8 b, f32x16 c) { return __builtin_amdgcn_mfma_f32_32x32x16_bf16(a, b, c, 0, 0, 0); }
; DI float half_max(float v) { auto rr = __builtin_amdgcn_permlane32_swap(__float_as_uint(v), __float_as_uint(v), false, false); return fmaxf(__uint_as_float(rr[0]), __uint_as_float(rr[1])); }
; template <int DVB, bool MASKED = true>
; DI void attn_step32(const bf16* Kt, int KP, const bf16* Vt, int VP, const bf16x8 (&qf)[4], f32x16 (&o)[DVB], float& m, float& l, unsigned vmask, float c2, int lane) {
;   const int r32 = lane & 31, h = lane >> 5;
;   f32x16 s;
; #pragma unroll
;   for (int i = 0; i < 16; ++i) s[i] = 0.f;
; #pragma unroll
;   for (int t = 0; t < 4; ++t) { const bf16x8 kf = *(const bf16x8*)(Kt + r32 * KP + t * 16 + h * 8); s = mfma32(kf, qf[t], s); }
;   float mx = -INFINITY;
; #pragma unroll
;   for (int i = 0; i < 16; ++i) { if (MASKED) { s[i] = ((vmask >> i) & 1u) ? s[i] : -INFINITY; } mx = fmaxf(mx, s[i]); }
;   mx = half_max(mx);
;   const float mxs = mx * c2;
;   if (__any(mxs > m + 6.f)) {
;     const float mn = fmaxf(m, mxs);
;     const float alpha = fexp2(m - mn); l *= alpha;
; #pragma unroll
;     for (int d = 0; d < DVB; ++d)
; #pragma unroll
;       for (int i = 0; i < 16; ++i) o[d][i] *= alpha;
;     m = mn;
;   }
; DI unsigned row_range_mask(int lo, int hi) {
;   lo = lo < 0 ? 0 : lo; hi = hi > 31 ? 31 : hi;
;   if (hi < lo) return 0u;
;   const unsigned upto_hi = (hi >= 31) ? 0xffffffffu : ((1u << (hi + 1)) - 1u);
;   return upto_hi & ~((1u << lo) - 1u);
; }
; DI unsigned lane_rows(unsigned m32, int h) {
;   const unsigned t = m32 >> (4 * h);
;   return (t & 0xFu) | ((t >> 4) & 0xF0u) | ((t >> 8) & 0xF00u) | ((t >> 12) & 0xF000u);
; }
.LBB0_2180:
	ds_read_b128 v[34:37], v120
	ds_read_b128 v[130:133], v120 offset:32
	ds_read_b128 v[134:137], v120 offset:64
	ds_read_b128 v[138:141], v120 offset:96
	v_min_i32_e32 v142, 31, v128
	v_add_u32_e32 v143, 1, v142
	v_add_u32_e32 v0, v127, v128
	v_lshlrev_b32_e64 v143, v143, -1
	v_max_i32_e32 v0, 0, v0
	v_cmp_gt_u32_e32 vcc, 31, v128
	s_waitcnt lgkmcnt(3)
	v_mfma_f32_32x32x16_bf16 v[34:49], v[34:37], v[50:53], 0
	v_lshlrev_b32_e64 v144, v0, -1
	s_waitcnt lgkmcnt(2)
	v_mfma_f32_32x32x16_bf16 v[34:49], v[130:133], v[54:57], v[34:49]
	v_not_b32_e32 v130, v143
	v_cndmask_b32_e32 v130, -1, v130, vcc
	v_and_b32_e32 v130, v130, v144
	v_cmp_ge_i32_e32 vcc, v142, v0
	s_nop 1
	v_cndmask_b32_e32 v0, 0, v130, vcc
	s_waitcnt lgkmcnt(1)
	v_mfma_f32_32x32x16_bf16 v[34:49], v[134:137], v[58:61], v[34:49]
	v_lshrrev_b32_e32 v133, v100, v0
	s_nop 0
	s_nop 0
	s_nop 0
	s_nop 0
	v_and_b32_e32 v135, 8, v133
	v_and_b32_e32 v136, 0x100, v133
	s_waitcnt lgkmcnt(0)
	v_mfma_f32_32x32x16_bf16 v[34:49], v[138:141], v[62:65], v[34:49]
	v_and_b32_e32 v137, 0x200, v133
	v_and_b32_e32 v142, 0x400, v133
	s_nop 9
	v_bfe_i32 v253, v133, 0, 1
	v_bfi_b32 v132, v253, v34, v125
	s_nop 0
	s_nop 1
	v_bfe_i32 v253, v133, 1, 1
	v_bfi_b32 v131, v253, v35, v125
	s_nop 0
	s_nop 1
	v_bfe_i32 v253, v133, 2, 1
	v_bfi_b32 v130, v253, v36, v125
	v_cmp_ne_u32_e32 vcc, 0, v135
	s_nop 1
	v_cndmask_b32_e32 v36, v125, v37, vcc
	v_cmp_ne_u32_e32 vcc, 0, v136
	v_max3_f32 v37, v132, s21, v131
	v_max3_f32 v37, v37, v130, v36
	v_cndmask_b32_e32 v35, v125, v38, vcc
	v_cmp_ne_u32_e32 vcc, 0, v137
	s_nop 1
	v_cndmask_b32_e32 v34, v125, v39, vcc
	v_cmp_ne_u32_e32 vcc, 0, v142
	v_max3_f32 v38, v37, v35, v34
	v_cndmask_b32_e32 v0, v125, v40, vcc
	s_nop 0
	v_bfe_i32 v253, v133, 11, 1
	v_bfi_b32 v37, v253, v41, v125
	v_max3_f32 v40, v38, v0, v37
	s_nop 0
	v_bfe_i32 v253, v133, 16, 1
	v_bfi_b32 v38, v253, v42, v125
	s_nop 1
	v_bfe_i32 v253, v133, 17, 1
	v_bfi_b32 v39, v253, v43, v125
	v_max3_f32 v42, v40, v38, v39
	s_nop 0
	v_bfe_i32 v253, v133, 18, 1
	v_bfi_b32 v40, v253, v44, v125
	s_nop 1
	v_bfe_i32 v253, v133, 19, 1
	v_bfi_b32 v41, v253, v45, v125
	v_max3_f32 v44, v42, v40, v41
	s_nop 0
	v_bfe_i32 v253, v133, 24, 1
	v_bfi_b32 v42, v253, v46, v125
	s_nop 1
	v_bfe_i32 v253, v133, 25, 1
	v_bfi_b32 v43, v253, v47, v125
	v_max3_f32 v46, v44, v42, v43
	s_nop 1
	v_bfe_i32 v253, v133, 26, 1
	v_bfi_b32 v44, v253, v48, v125
	s_nop 1
	v_bfe_i32 v253, v133, 27, 1
	v_bfi_b32 v45, v253, v49, v125
	v_max3_f32 v46, v46, v44, v45
	v_mov_b32_e32 v47, v46
	s_nop 1
	v_permlane32_swap_b32_e32 v46, v47
	v_max_f32_e32 v47, v47, v47
	v_max_f32_e32 v46, v46, v46
	v_max_f32_e32 v46, v46, v47
	v_mul_f32_e32 v46, 0x3e38aa3b, v46
	v_add_f32_e32 v47, 0x40c00000, v129
	v_cmp_gt_f32_e32 vcc, v46, v47
	s_cbranch_vccz .LBB0_2177
	v_max_f32_e32 v46, v46, v46
	v_max_f32_e32 v47, v129, v129
	v_max_f32_e32 v47, v47, v46
	v_sub_f32_e32 v46, v129, v47
	v_exp_f32_e32 v46, v46
	v_mov_b32_e32 v129, v47
	v_mul_f32_e32 v126, v126, v46
	v_pk_mul_f32 v[32:33], v[32:33], v[46:47] op_sel_hi:[1,0]
	v_pk_mul_f32 v[30:31], v[30:31], v[46:47] op_sel_hi:[1,0]
	v_pk_mul_f32 v[28:29], v[28:29], v[46:47] op_sel_hi:[1,0]
	v_pk_mul_f32 v[26:27], v[26:27], v[46:47] op_sel_hi:[1,0]
	v_pk_mul_f32 v[24:25], v[24:25], v[46:47] op_sel_hi:[1,0]
	v_pk_mul_f32 v[22:23], v[22:23], v[46:47] op_sel_hi:[1,0]
	v_pk_mul_f32 v[20:21], v[20:21], v[46:47] op_sel_hi:[1,0]
	v_pk_mul_f32 v[18:19], v[18:19], v[46:47] op_sel_hi:[1,0]
	v_pk_mul_f32 v[16:17], v[16:17], v[46:47] op_sel_hi:[1,0]
	v_pk_mul_f32 v[14:15], v[14:15], v[46:47] op_sel_hi:[1,0]
	v_pk_mul_f32 v[12:13], v[12:13], v[46:47] op_sel_hi:[1,0]
	v_pk_mul_f32 v[10:11], v[10:11], v[46:47] op_sel_hi:[1,0]
	v_pk_mul_f32 v[8:9], v[8:9], v[46:47] op_sel_hi:[1,0]
	v_pk_mul_f32 v[6:7], v[6:7], v[46:47] op_sel_hi:[1,0]
	v_pk_mul_f32 v[4:5], v[4:5], v[46:47] op_sel_hi:[1,0]
	v_pk_mul_f32 v[2:3], v[2:3], v[46:47] op_sel_hi:[1,0]
	s_branch .LBB0_2177

; __device__ __forceinline__ unsigned xb_ld(unsigned* p)              { return __hip_atomic_load(p, __ATOMIC_RELAXED, __HIP_MEMORY_SCOPE_AGENT); }
; __device__ __forceinline__ unsigned xb_add(unsigned* p, unsigned v) { return __hip_atomic_fetch_add(p, v, __ATOMIC_RELAXED, __HIP_MEMORY_SCOPE_AGENT); }
; #define XB_SPIN(cond, bar) do { unsigned _sp = 0; while (cond) { __builtin_amdgcn_s_sleep(1); \
;     if ((++_sp & 255u) == 0u) { if (xb_ld(&(bar)[XB_TMO])) break; if (_sp > XB_SPIN_CAP) { atomicAdd(&(bar)[XB_TMO], 1u); break; } } } } while (0)
; __device__ __forceinline__ void xcd_barrier(const XcdBarrier& b) {
;     ...
;         const unsigned old = xb_add(&bar[XB_XSUB(b.x)], 1u);
;         const unsigned gen = old / nloc;
;         if (old + 1u == (gen + 1u) * nloc) {
;             __builtin_amdgcn_fence(__ATOMIC_RELEASE, "agent");
;             asm volatile("s_waitcnt vmcnt(0)" ::: "memory");
;             const unsigned og = xb_add(&bar[XB_TOP], 1u);
;             const unsigned tg = og / nx;
;             if (og + 1u == (tg + 1u) * nx) xb_add(&bar[XB_TOPGEN], 1u);
;             else XB_SPIN(xb_ld(&bar[XB_TOPGEN]) == tg, bar);
;             __builtin_amdgcn_fence(__ATOMIC_ACQUIRE, "agent");
;             xb_add(&bar[XB_XGEN(b.x)], 1u);
;             asm volatile("s_waitcnt vmcnt(0)" ::: "memory");
;         } else {
;             XB_SPIN(xb_ld(&bar[XB_XGEN(b.x)]) == gen, bar);
;             __builtin_amdgcn_fence(__ATOMIC_ACQUIRE, "agent");
;             asm volatile("s_waitcnt vmcnt(0)" ::: "memory");
;         }
.LBB0_2573:
	s_or_b64 exec, exec, s[6:7]
	s_mov_b64 s[6:7], exec
	v_mbcnt_lo_u32_b32 v0, s6, 0
	v_mbcnt_hi_u32_b32 v0, s7, v0
	v_cmp_eq_u32_e32 vcc, 0, v0
	s_waitcnt vmcnt(0)
	buffer_inv sc1
	s_and_saveexec_b64 s[8:9], vcc
	s_cbranch_execz .LBB0_2575
	s_bcnt1_i32_b64 s6, s[6:7]
	v_mov_b32_e32 v0, 0x2000
	v_mov_b32_e32 v1, s6
	global_atomic_add v0, v1, s[2:3] offset:1024
	s_nop 0
	s_nop 0
	s_nop 0
	s_nop 0
	s_nop 0
	s_nop 0
	s_nop 0
	s_nop 0
	s_nop 0
	s_nop 0
	s_nop 0
	s_nop 0
	s_nop 0
	s_nop 0
	s_nop 0
	s_nop 0
	s_nop 0
	s_nop 0
	s_nop 0
	s_nop 0
	s_nop 0

; DI float fexp2(float x) { return __builtin_amdgcn_exp2f(x); }
; DI f32x16 mfma32(bf16x8 a, bf16x8 b, f32x16 c) { return __builtin_amdgcn_mfma_f32_32x32x16_bf16(a, b, c, 0, 0, 0); }
; DI int crow(int i, int h) { return (i & 3) + 8 * (i >> 2) + 4 * h; }
; DI float half_max(float v) { auto rr = __builtin_amdgcn_permlane32_swap(__float_as_uint(v), __float_as_uint(v), false, false); return fmaxf(__uint_as_float(rr[0]), __uint_as_float(rr[1])); }
; template <int DVB, bool MASKED = true>
; DI void attn_step32(const bf16* Kt, int KP, const bf16* Vt, int VP, const bf16x8 (&qf)[4], f32x16 (&o)[DVB], float& m, float& l, unsigned vmask, float c2, int lane) {
;     ...
;   for (int t = 0; t < 4; ++t) { const bf16x8 kf = *(const bf16x8*)(Kt + r32 * KP + t * 16 + h * 8); s = mfma32(kf, qf[t], s); }
;   float mx = -INFINITY;
; #pragma unroll
;   for (int i = 0; i < 16; ++i) { if (MASKED) { s[i] = ((vmask >> i) & 1u) ? s[i] : -INFINITY; } mx = fmaxf(mx, s[i]); }
;   mx = half_max(mx);
;   const float mxs = mx * c2;
;   if (__any(mxs > m + 6.f)) {
;     const float mn = fmaxf(m, mxs);
;     const float alpha = fexp2(m - mn); l *= alpha;
; #pragma unroll
;     for (int d = 0; d < DVB; ++d)
; #pragma unroll
;       for (int i = 0; i < 16; ++i) o[d][i] *= alpha;
;     m = mn;
;   }
; DI void mixerD_unit(const Params& p, int b, int head, int qb, char* lds) {
;     ...
;           unsigned vm = 0;
; #pragma unroll
;           for (int i = 0; i < 16; ++i) if (k0 + crow(i, h) <= qpos) vm |= (1u << i);
;           attn_step32<4, true>(Ks + sub * 32 * DKP, DKP, Vs + sub * 32 * DVP, DVP, qf, o, m, l, vm, 0.125f * LOG2E, lane);
.LBB0_2593:
	s_andn2_saveexec_b64 s[2:3], s[2:3]
	s_cbranch_execz .LBB0_2597
	v_add_u32_e32 v160, s65, v146
	v_subrev_u32_e32 v161, 32, v160
	v_subrev_u32_e32 v71, 22, v160
	v_subrev_u32_e32 v72, 21, v160
	v_cmp_lt_i32_e32 vcc, v161, v122
	v_subrev_u32_e32 v67, 30, v160
	v_subrev_u32_e32 v68, 29, v160
	v_cmp_gt_i32_e64 s[16:17], v71, v122
	v_cmp_gt_i32_e64 s[18:19], v72, v122
	v_cndmask_b32_e64 v66, 0, 2, vcc
	v_cmp_gt_i32_e64 s[8:9], v67, v122
	v_cmp_gt_i32_e64 s[10:11], v68, v122
	v_subrev_u32_e32 v69, 24, v160
	v_subrev_u32_e32 v70, 23, v160
	v_cndmask_b32_e64 v71, 64, 0, s[16:17]
	v_cndmask_b32_e64 v72, v140, 0, s[18:19]
	v_cndmask_b32_e64 v67, 4, 0, s[8:9]
	v_cndmask_b32_e64 v68, 8, 0, s[10:11]
	v_cmp_gt_i32_e64 s[12:13], v69, v122
	v_cmp_gt_i32_e64 s[14:15], v70, v122
	v_or3_b32 v66, v66, v71, v72
	v_cndmask_b32_e64 v69, 16, 0, s[12:13]
	v_cndmask_b32_e64 v70, 32, 0, s[14:15]
	v_or3_b32 v66, v67, v68, v66
	v_or3_b32 v70, v69, v70, v66
	ds_read_b128 v[66:69], v155
	ds_read_b128 v[156:159], v155 offset:32
	v_add_u32_e32 v71, -16, v160
	v_add_u32_e32 v72, -15, v160
	v_cmp_gt_i32_e64 s[20:21], v71, v122
	v_cmp_gt_i32_e64 s[22:23], v72, v122
	v_add_u32_e32 v164, -14, v160
	v_cndmask_b32_e64 v71, v141, 0, s[20:21]
	v_cndmask_b32_e64 v72, v142, 0, s[22:23]
	v_or3_b32 v162, v71, v70, v72
	s_waitcnt lgkmcnt(1)
	v_mfma_f32_32x32x16_bf16 v[66:81], v[66:69], v[90:93], 0
	v_cmp_gt_i32_e64 s[24:25], v164, v122
	v_add_u32_e32 v165, -13, v160
	s_nop 0
	v_cndmask_b32_e64 v164, v127, 0, s[24:25]
	v_cmp_gt_i32_e64 s[24:25], v165, v122
	s_nop 1
	v_cndmask_b32_e64 v165, v134, 0, s[24:25]
	v_or3_b32 v168, v164, v165, v162
	ds_read_b128 v[164:167], v155 offset:64
	s_waitcnt lgkmcnt(1)
	v_mfma_f32_32x32x16_bf16 v[66:81], v[156:159], v[82:85], v[66:81]
	v_add_u32_e32 v162, -8, v160
	v_cmp_gt_i32_e64 s[24:25], v162, v122
	v_add_u32_e32 v157, -7, v160
	v_add_u32_e32 v162, -6, v160
	v_cndmask_b32_e64 v156, v135, 0, s[24:25]
	v_cmp_gt_i32_e64 s[24:25], v157, v122
	v_add_u32_e32 v160, -5, v160
	s_nop 0
	v_cndmask_b32_e64 v157, v136, 0, s[24:25]
	v_or3_b32 v169, v156, v157, v168
	ds_read_b128 v[156:159], v155 offset:96
	s_waitcnt lgkmcnt(1)
	v_mfma_f32_32x32x16_bf16 v[66:81], v[164:167], v[86:89], v[66:81]
	v_cmp_gt_i32_e64 s[24:25], v162, v122
	s_nop 1
	v_cndmask_b32_e64 v162, v137, 0, s[24:25]
	v_cmp_gt_i32_e64 s[24:25], v160, v122
	s_waitcnt lgkmcnt(0)
	v_mfma_f32_32x32x16_bf16 v[66:81], v[156:159], v[94:97], v[66:81]
	v_cndmask_b32_e64 v160, v138, 0, s[24:25]
	v_cmp_le_i32_e64 s[24:25], v161, v122
	v_or3_b32 v164, v162, v160, v169
	s_nop 8
	v_cndmask_b32_e64 v162, v143, v66, s[24:25]
	v_cndmask_b32_e32 v161, v143, v67, vcc
	v_max3_f32 v66, v162, s56, v161
	v_cndmask_b32_e64 v160, v68, v143, s[8:9]
	v_cndmask_b32_e64 v159, v69, v143, s[10:11]
	v_max3_f32 v66, v66, v160, v159
	v_cndmask_b32_e64 v158, v70, v143, s[12:13]
	v_cndmask_b32_e64 v157, v71, v143, s[14:15]
	v_max3_f32 v66, v66, v158, v157
	v_cndmask_b32_e64 v156, v72, v143, s[16:17]
	v_cndmask_b32_e64 v72, v73, v143, s[18:19]
	v_max3_f32 v67, v66, v156, v72
	v_cndmask_b32_e64 v69, v74, v143, s[20:21]
	v_cndmask_b32_e64 v66, v75, v143, s[22:23]
	v_max3_f32 v70, v67, v69, v66
	v_bfe_i32 v253, v168, 10, 1
	v_bfi_b32 v67, v253, v76, v143
	v_and_b32_e32 v74, 0x8000, v164
	s_nop 0
	v_bfe_i32 v253, v168, 11, 1
	v_bfi_b32 v68, v253, v77, v143
	v_max3_f32 v73, v70, v67, v68
	s_nop 1
	v_bfe_i32 v253, v169, 12, 1
	v_bfi_b32 v70, v253, v78, v143
	s_nop 1
	v_bfe_i32 v253, v169, 13, 1
	v_bfi_b32 v71, v253, v79, v143
	v_max3_f32 v75, v73, v70, v71
	s_nop 1
	v_bfe_i32 v253, v164, 14, 1
	v_bfi_b32 v73, v253, v80, v143
	v_cmp_ne_u32_e32 vcc, 0, v74
	s_nop 1
	v_cndmask_b32_e32 v74, v143, v81, vcc
	v_max3_f32 v75, v75, v73, v74
	v_mov_b32_e32 v76, v75
	s_nop 1
	v_permlane32_swap_b32_e32 v75, v76
	v_max_f32_e32 v76, v76, v76
	v_max_f32_e32 v75, v75, v75
	v_max_f32_e32 v75, v75, v76
	v_mul_f32_e32 v75, 0x3e38aa3b, v75
	v_cmp_gt_f32_e32 vcc, v75, v163
	s_cbranch_vccz .LBB0_2596
	v_max_f32_e32 v75, v75, v75
	v_max_f32_e32 v76, v154, v154
	v_max_f32_e32 v75, v76, v75
	v_sub_f32_e32 v76, v154, v75
	v_exp_f32_e32 v76, v76
	v_mov_b32_e32 v154, v75
	v_mul_f32_e32 v64, v64, v76
	v_pk_mul_f32 v[62:63], v[62:63], v[76:77] op_sel_hi:[1,0]
	v_pk_mul_f32 v[60:61], v[60:61], v[76:77] op_sel_hi:[1,0]
	v_pk_mul_f32 v[58:59], v[58:59], v[76:77] op_sel_hi:[1,0]
	v_pk_mul_f32 v[56:57], v[56:57], v[76:77] op_sel_hi:[1,0]
	v_pk_mul_f32 v[54:55], v[54:55], v[76:77] op_sel_hi:[1,0]
	v_pk_mul_f32 v[52:53], v[52:53], v[76:77] op_sel_hi:[1,0]
	v_pk_mul_f32 v[50:51], v[50:51], v[76:77] op_sel_hi:[1,0]
	v_pk_mul_f32 v[48:49], v[48:49], v[76:77] op_sel_hi:[1,0]
	v_pk_mul_f32 v[46:47], v[46:47], v[76:77] op_sel_hi:[1,0]
	v_pk_mul_f32 v[44:45], v[44:45], v[76:77] op_sel_hi:[1,0]
	v_pk_mul_f32 v[42:43], v[42:43], v[76:77] op_sel_hi:[1,0]
	v_pk_mul_f32 v[40:41], v[40:41], v[76:77] op_sel_hi:[1,0]
	v_pk_mul_f32 v[38:39], v[38:39], v[76:77] op_sel_hi:[1,0]
	v_pk_mul_f32 v[36:37], v[36:37], v[76:77] op_sel_hi:[1,0]
	v_pk_mul_f32 v[34:35], v[34:35], v[76:77] op_sel_hi:[1,0]
	v_pk_mul_f32 v[32:33], v[32:33], v[76:77] op_sel_hi:[1,0]
	v_pk_mul_f32 v[30:31], v[30:31], v[76:77] op_sel_hi:[1,0]
	v_pk_mul_f32 v[28:29], v[28:29], v[76:77] op_sel_hi:[1,0]
	v_pk_mul_f32 v[26:27], v[26:27], v[76:77] op_sel_hi:[1,0]
	v_pk_mul_f32 v[24:25], v[24:25], v[76:77] op_sel_hi:[1,0]
	v_pk_mul_f32 v[22:23], v[22:23], v[76:77] op_sel_hi:[1,0]
	v_pk_mul_f32 v[20:21], v[20:21], v[76:77] op_sel_hi:[1,0]
	v_pk_mul_f32 v[18:19], v[18:19], v[76:77] op_sel_hi:[1,0]
	v_pk_mul_f32 v[16:17], v[16:17], v[76:77] op_sel_hi:[1,0]
	v_pk_mul_f32 v[14:15], v[14:15], v[76:77] op_sel_hi:[1,0]
	v_pk_mul_f32 v[12:13], v[12:13], v[76:77] op_sel_hi:[1,0]
	v_pk_mul_f32 v[10:11], v[10:11], v[76:77] op_sel_hi:[1,0]
	v_pk_mul_f32 v[8:9], v[8:9], v[76:77] op_sel_hi:[1,0]
	v_pk_mul_f32 v[6:7], v[6:7], v[76:77] op_sel_hi:[1,0]
	v_pk_mul_f32 v[4:5], v[4:5], v[76:77] op_sel_hi:[1,0]
	v_pk_mul_f32 v[2:3], v[2:3], v[76:77] op_sel_hi:[1,0]
	v_pk_mul_f32 v[0:1], v[0:1], v[76:77] op_sel_hi:[1,0]

; DI float fexp2(float x) { return __builtin_amdgcn_exp2f(x); }
; DI f32x16 mfma32(bf16x8 a, bf16x8 b, f32x16 c) { return __builtin_amdgcn_mfma_f32_32x32x16_bf16(a, b, c, 0, 0, 0); }
; DI int crow(int i, int h) { return (i & 3) + 8 * (i >> 2) + 4 * h; }
; DI float half_max(float v) { auto rr = __builtin_amdgcn_permlane32_swap(__float_as_uint(v), __float_as_uint(v), false, false); return fmaxf(__uint_as_float(rr[0]), __uint_as_float(rr[1])); }
; template <int DVB, bool MASKED = true>
; DI void attn_step32(const bf16* Kt, int KP, const bf16* Vt, int VP, const bf16x8 (&qf)[4], f32x16 (&o)[DVB], float& m, float& l, unsigned vmask, float c2, int lane) {
;     ...
;   for (int t = 0; t < 4; ++t) { const bf16x8 kf = *(const bf16x8*)(Kt + r32 * KP + t * 16 + h * 8); s = mfma32(kf, qf[t], s); }
;   float mx = -INFINITY;
; #pragma unroll
;   for (int i = 0; i < 16; ++i) { if (MASKED) { s[i] = ((vmask >> i) & 1u) ? s[i] : -INFINITY; } mx = fmaxf(mx, s[i]); }
;   mx = half_max(mx);
;   const float mxs = mx * c2;
;   if (__any(mxs > m + 6.f)) {
;     const float mn = fmaxf(m, mxs);
;     const float alpha = fexp2(m - mn); l *= alpha;
; #pragma unroll
;     for (int d = 0; d < DVB; ++d)
; #pragma unroll
;       for (int i = 0; i < 16; ++i) o[d][i] *= alpha;
;     m = mn;
;   }
; DI void mixerD_unit(const Params& p, int b, int head, int qb, char* lds) {
;     ...
;           unsigned vm = 0;
; #pragma unroll
;           for (int i = 0; i < 16; ++i) if (k0 + crow(i, h) <= qpos) vm |= (1u << i);
;           attn_step32<4, true>(Ks + sub * 32 * DKP, DKP, Vs + sub * 32 * DVP, DVP, qf, o, m, l, vm, 0.125f * LOG2E, lane);
.LBB0_2603:
	s_andn2_saveexec_b64 s[2:3], s[2:3]
	s_cbranch_execz .LBB0_2584
	v_add_u32_e32 v160, s65, v146
	v_add_u32_e32 v71, 10, v160
	v_add_u32_e32 v72, 11, v160
	v_cmp_lt_i32_e32 vcc, v160, v122
	v_add_u32_e32 v67, 2, v160
	v_add_u32_e32 v68, 3, v160
	v_cmp_gt_i32_e64 s[16:17], v71, v122
	v_cmp_gt_i32_e64 s[18:19], v72, v122
	v_cndmask_b32_e64 v66, 0, 2, vcc
	v_cmp_gt_i32_e64 s[8:9], v67, v122
	v_cmp_gt_i32_e64 s[10:11], v68, v122
	v_add_u32_e32 v69, 8, v160
	v_add_u32_e32 v70, 9, v160
	v_cndmask_b32_e64 v71, 64, 0, s[16:17]
	v_cndmask_b32_e64 v72, v140, 0, s[18:19]
	v_cndmask_b32_e64 v67, 4, 0, s[8:9]
	v_cndmask_b32_e64 v68, 8, 0, s[10:11]
	v_cmp_gt_i32_e64 s[12:13], v69, v122
	v_cmp_gt_i32_e64 s[14:15], v70, v122
	v_or3_b32 v66, v66, v71, v72
	v_cndmask_b32_e64 v69, 16, 0, s[12:13]
	v_cndmask_b32_e64 v70, 32, 0, s[14:15]
	v_or3_b32 v66, v67, v68, v66
	v_or3_b32 v70, v69, v70, v66
	ds_read_b128 v[66:69], v155 offset:4608
	ds_read_b128 v[156:159], v155 offset:4640
	v_add_u32_e32 v71, 16, v160
	v_add_u32_e32 v72, 17, v160
	v_cmp_gt_i32_e64 s[20:21], v71, v122
	v_cmp_gt_i32_e64 s[22:23], v72, v122
	v_add_u32_e32 v163, 18, v160
	v_cndmask_b32_e64 v71, v141, 0, s[20:21]
	v_cndmask_b32_e64 v72, v142, 0, s[22:23]
	v_or3_b32 v161, v71, v70, v72
	s_waitcnt lgkmcnt(1)
	v_mfma_f32_32x32x16_bf16 v[66:81], v[66:69], v[90:93], 0
	v_cmp_gt_i32_e64 s[24:25], v163, v122
	v_add_u32_e32 v164, 19, v160
	s_nop 0
	v_cndmask_b32_e64 v163, v127, 0, s[24:25]
	v_cmp_gt_i32_e64 s[24:25], v164, v122
	s_nop 1
	v_cndmask_b32_e64 v164, v134, 0, s[24:25]
	v_or3_b32 v163, v163, v164, v161
	ds_read_b128 v[164:167], v155 offset:4672
	s_waitcnt lgkmcnt(1)
	v_mfma_f32_32x32x16_bf16 v[66:81], v[156:159], v[82:85], v[66:81]
	v_add_u32_e32 v161, 24, v160
	v_cmp_gt_i32_e64 s[24:25], v161, v122
	v_add_u32_e32 v157, 25, v160
	v_add_u32_e32 v161, 27, v160
	v_cndmask_b32_e64 v156, v135, 0, s[24:25]
	v_cmp_gt_i32_e64 s[24:25], v157, v122
	s_nop 1
	v_cndmask_b32_e64 v157, v136, 0, s[24:25]
	v_or3_b32 v168, v156, v157, v163
	ds_read_b128 v[156:159], v155 offset:4704
	s_waitcnt lgkmcnt(1)
	v_mfma_f32_32x32x16_bf16 v[66:81], v[164:167], v[86:89], v[66:81]
	v_add_u32_e32 v155, 26, v160
	v_cmp_gt_i32_e64 s[24:25], v155, v122
	s_nop 1
	v_cndmask_b32_e64 v155, v137, 0, s[24:25]
	v_cmp_gt_i32_e64 s[24:25], v161, v122
	s_waitcnt lgkmcnt(0)
	v_mfma_f32_32x32x16_bf16 v[66:81], v[156:159], v[94:97], v[66:81]
	v_cndmask_b32_e64 v161, v138, 0, s[24:25]
	v_cmp_le_i32_e64 s[24:25], v160, v122
	v_or3_b32 v164, v155, v161, v168
	s_nop 8
	v_cndmask_b32_e64 v161, v143, v66, s[24:25]
	v_cndmask_b32_e32 v160, v143, v67, vcc
	v_max3_f32 v66, v161, s56, v160
	v_cndmask_b32_e64 v159, v68, v143, s[8:9]
	v_cndmask_b32_e64 v158, v69, v143, s[10:11]
	v_max3_f32 v66, v66, v159, v158
	v_cndmask_b32_e64 v157, v70, v143, s[12:13]
	v_cndmask_b32_e64 v156, v71, v143, s[14:15]
	v_max3_f32 v66, v66, v157, v156
	v_cndmask_b32_e64 v155, v72, v143, s[16:17]
	v_cndmask_b32_e64 v72, v73, v143, s[18:19]
	v_max3_f32 v67, v66, v155, v72
	v_cndmask_b32_e64 v69, v74, v143, s[20:21]
	v_cndmask_b32_e64 v66, v75, v143, s[22:23]
	v_max3_f32 v70, v67, v69, v66
	v_bfe_i32 v253, v163, 10, 1
	v_bfi_b32 v67, v253, v76, v143
	v_and_b32_e32 v74, 0x8000, v164
	s_nop 0
	v_bfe_i32 v253, v163, 11, 1
	v_bfi_b32 v68, v253, v77, v143
	v_max3_f32 v73, v70, v67, v68
	s_nop 1
	v_bfe_i32 v253, v168, 12, 1
	v_bfi_b32 v70, v253, v78, v143
	s_nop 1
	v_bfe_i32 v253, v168, 13, 1
	v_bfi_b32 v71, v253, v79, v143
	v_max3_f32 v75, v73, v70, v71
	s_nop 1
	v_bfe_i32 v253, v164, 14, 1
	v_bfi_b32 v73, v253, v80, v143
	v_cmp_ne_u32_e32 vcc, 0, v74
	s_nop 1
	v_cndmask_b32_e32 v74, v143, v81, vcc
	v_max3_f32 v75, v75, v73, v74
	v_mov_b32_e32 v76, v75
	s_nop 1
	v_permlane32_swap_b32_e32 v75, v76
	v_max_f32_e32 v76, v76, v76
	v_max_f32_e32 v75, v75, v75
	v_max_f32_e32 v75, v75, v76
	v_mul_f32_e32 v75, 0x3e38aa3b, v75
	v_cmp_gt_f32_e32 vcc, v75, v162
	s_cbranch_vccz .LBB0_2583
	v_max_f32_e32 v75, v75, v75
	v_max_f32_e32 v76, v154, v154
	v_max_f32_e32 v75, v76, v75
	v_sub_f32_e32 v76, v154, v75
	v_exp_f32_e32 v76, v76
	v_mov_b32_e32 v154, v75
	v_mul_f32_e32 v64, v64, v76
	v_pk_mul_f32 v[62:63], v[62:63], v[76:77] op_sel_hi:[1,0]
	v_pk_mul_f32 v[60:61], v[60:61], v[76:77] op_sel_hi:[1,0]
	v_pk_mul_f32 v[58:59], v[58:59], v[76:77] op_sel_hi:[1,0]
	v_pk_mul_f32 v[56:57], v[56:57], v[76:77] op_sel_hi:[1,0]
	v_pk_mul_f32 v[54:55], v[54:55], v[76:77] op_sel_hi:[1,0]
	v_pk_mul_f32 v[52:53], v[52:53], v[76:77] op_sel_hi:[1,0]
	v_pk_mul_f32 v[50:51], v[50:51], v[76:77] op_sel_hi:[1,0]
	v_pk_mul_f32 v[48:49], v[48:49], v[76:77] op_sel_hi:[1,0]
	v_pk_mul_f32 v[46:47], v[46:47], v[76:77] op_sel_hi:[1,0]
	v_pk_mul_f32 v[44:45], v[44:45], v[76:77] op_sel_hi:[1,0]
	v_pk_mul_f32 v[42:43], v[42:43], v[76:77] op_sel_hi:[1,0]
	v_pk_mul_f32 v[40:41], v[40:41], v[76:77] op_sel_hi:[1,0]
	v_pk_mul_f32 v[38:39], v[38:39], v[76:77] op_sel_hi:[1,0]
	v_pk_mul_f32 v[36:37], v[36:37], v[76:77] op_sel_hi:[1,0]
	v_pk_mul_f32 v[34:35], v[34:35], v[76:77] op_sel_hi:[1,0]
	v_pk_mul_f32 v[32:33], v[32:33], v[76:77] op_sel_hi:[1,0]
	v_pk_mul_f32 v[30:31], v[30:31], v[76:77] op_sel_hi:[1,0]
	v_pk_mul_f32 v[28:29], v[28:29], v[76:77] op_sel_hi:[1,0]
	v_pk_mul_f32 v[26:27], v[26:27], v[76:77] op_sel_hi:[1,0]
	v_pk_mul_f32 v[24:25], v[24:25], v[76:77] op_sel_hi:[1,0]
	v_pk_mul_f32 v[22:23], v[22:23], v[76:77] op_sel_hi:[1,0]
	v_pk_mul_f32 v[20:21], v[20:21], v[76:77] op_sel_hi:[1,0]
	v_pk_mul_f32 v[18:19], v[18:19], v[76:77] op_sel_hi:[1,0]
	v_pk_mul_f32 v[16:17], v[16:17], v[76:77] op_sel_hi:[1,0]
	v_pk_mul_f32 v[14:15], v[14:15], v[76:77] op_sel_hi:[1,0]
	v_pk_mul_f32 v[12:13], v[12:13], v[76:77] op_sel_hi:[1,0]
	v_pk_mul_f32 v[10:11], v[10:11], v[76:77] op_sel_hi:[1,0]
	v_pk_mul_f32 v[8:9], v[8:9], v[76:77] op_sel_hi:[1,0]
	v_pk_mul_f32 v[6:7], v[6:7], v[76:77] op_sel_hi:[1,0]
	v_pk_mul_f32 v[4:5], v[4:5], v[76:77] op_sel_hi:[1,0]
	v_pk_mul_f32 v[2:3], v[2:3], v[76:77] op_sel_hi:[1,0]
	v_pk_mul_f32 v[0:1], v[0:1], v[76:77] op_sel_hi:[1,0]
	s_branch .LBB0_2583

; DI float fexp2(float x) { return __builtin_amdgcn_exp2f(x); }
; DI f32x16 mfma32(bf16x8 a, bf16x8 b, f32x16 c) { return __builtin_amdgcn_mfma_f32_32x32x16_bf16(a, b, c, 0, 0, 0); }
; DI float half_max(float v) { auto rr = __builtin_amdgcn_permlane32_swap(__float_as_uint(v), __float_as_uint(v), false, false); return fmaxf(__uint_as_float(rr[0]), __uint_as_float(rr[1])); }
; template <int DVB, bool MASKED = true>
; DI void attn_step32(const bf16* Kt, int KP, const bf16* Vt, int VP, const bf16x8 (&qf)[4], f32x16 (&o)[DVB], float& m, float& l, unsigned vmask, float c2, int lane) {
;   const int r32 = lane & 31, h = lane >> 5;
;   f32x16 s;
; #pragma unroll
;   for (int i = 0; i < 16; ++i) s[i] = 0.f;
; #pragma unroll
;   for (int t = 0; t < 4; ++t) { const bf16x8 kf = *(const bf16x8*)(Kt + r32 * KP + t * 16 + h * 8); s = mfma32(kf, qf[t], s); }
;   float mx = -INFINITY;
; #pragma unroll
;   for (int i = 0; i < 16; ++i) { if (MASKED) { s[i] = ((vmask >> i) & 1u) ? s[i] : -INFINITY; } mx = fmaxf(mx, s[i]); }
;   mx = half_max(mx);
;   const float mxs = mx * c2;
;   if (__any(mxs > m + 6.f)) {
;     const float mn = fmaxf(m, mxs);
;     const float alpha = fexp2(m - mn); l *= alpha;
; #pragma unroll
;     for (int d = 0; d < DVB; ++d)
; #pragma unroll
;       for (int i = 0; i < 16; ++i) o[d][i] *= alpha;
;     m = mn;
;   }
; DI unsigned row_range_mask(int lo, int hi) {
;   lo = lo < 0 ? 0 : lo; hi = hi > 31 ? 31 : hi;
;   if (hi < lo) return 0u;
;   const unsigned upto_hi = (hi >= 31) ? 0xffffffffu : ((1u << (hi + 1)) - 1u);
;   return upto_hi & ~((1u << lo) - 1u);
; }
; DI unsigned lane_rows(unsigned m32, int h) {
;   const unsigned t = m32 >> (4 * h);
;   return (t & 0xFu) | ((t >> 4) & 0xF0u) | ((t >> 8) & 0xF00u) | ((t >> 12) & 0xF000u);
; }
.LBB0_2615:
	s_waitcnt lgkmcnt(0)
	s_waitcnt vmcnt(7)
	ds_write_b128 v113, v[66:69]
	s_waitcnt vmcnt(6)
	ds_write_b128 v113, v[70:73] offset:4608
	s_waitcnt vmcnt(5)
	ds_write_b128 v113, v[74:77] offset:1152
	s_waitcnt vmcnt(4)
	ds_write_b128 v113, v[78:81] offset:5760
	s_waitcnt vmcnt(3)
	ds_write_b128 v113, v[82:85] offset:2304
	s_waitcnt vmcnt(2)
	ds_write_b128 v113, v[86:89] offset:6912
	s_waitcnt vmcnt(1)
	ds_write_b128 v113, v[94:97] offset:3456
	s_waitcnt vmcnt(0)
	ds_write_b128 v113, v[90:93] offset:8064
	s_waitcnt lgkmcnt(0)
	ds_read_b128 v[34:37], v114
	ds_read_b128 v[66:69], v114 offset:32
	v_max_i32_e32 v0, 0x80, v103
	s_waitcnt lgkmcnt(1)
	v_mfma_f32_32x32x16_bf16 v[34:49], v[34:37], v[62:65], 0
	v_add_u32_e32 v62, 0x260, v126
	v_sub_u32_e32 v0, v0, v62
	v_sub_u32_e32 v70, v103, v62
	ds_read_b128 v[62:65], v114 offset:64
	v_min_i32_e32 v71, 31, v70
	v_cmp_gt_i32_e32 vcc, 31, v70
	v_add_u32_e32 v0, 0xffffff80, v0
	s_waitcnt lgkmcnt(1)
	v_mfma_f32_32x32x16_bf16 v[34:49], v[66:69], v[58:61], v[34:49]
	v_add_u32_e32 v58, 1, v71
	v_lshlrev_b32_e64 v58, v58, -1
	v_not_b32_e32 v58, v58
	v_cndmask_b32_e32 v66, -1, v58, vcc
	ds_read_b128 v[58:61], v114 offset:96
	v_max_i32_e32 v0, 0, v0
	v_lshlrev_b32_e64 v67, v0, -1
	s_waitcnt lgkmcnt(1)
	v_mfma_f32_32x32x16_bf16 v[34:49], v[62:65], v[54:57], v[34:49]
	v_and_b32_e32 v54, v66, v67
	v_cmp_ge_i32_e32 vcc, v71, v0
	s_nop 1
	v_cndmask_b32_e32 v0, 0, v54, vcc
	v_lshrrev_b32_e32 v0, v98, v0
	s_nop 0
	s_waitcnt lgkmcnt(0)
	v_mfma_f32_32x32x16_bf16 v[34:49], v[58:61], v[50:53], v[34:49]
	s_nop 0
	s_nop 0
	s_nop 0
	s_nop 8
	v_bfe_i32 v253, v0, 0, 1
	v_bfi_b32 v56, v253, v34, v123
	s_nop 0
	s_nop 1
	v_bfe_i32 v253, v0, 1, 1
	v_bfi_b32 v53, v253, v35, v123
	v_max3_f32 v34, v56, s2, v53
	v_bfe_i32 v253, v0, 2, 1
	v_bfi_b32 v54, v253, v36, v123
	v_bfe_i32 v253, v0, 3, 1
	v_bfi_b32 v50, v253, v37, v123
	v_max3_f32 v34, v34, v54, v50
	v_bfe_i32 v253, v0, 8, 1
	v_bfi_b32 v51, v253, v38, v123
	v_bfe_i32 v253, v0, 9, 1
	v_bfi_b32 v52, v253, v39, v123
	v_max3_f32 v34, v34, v51, v52
	v_bfe_i32 v253, v0, 10, 1
	v_bfi_b32 v55, v253, v40, v123
	v_bfe_i32 v253, v0, 11, 1
	v_bfi_b32 v39, v253, v41, v123
	v_max3_f32 v34, v34, v55, v39
	v_bfe_i32 v253, v0, 16, 1
	v_bfi_b32 v40, v253, v42, v123
	v_bfe_i32 v253, v0, 17, 1
	v_bfi_b32 v41, v253, v43, v123
	v_max3_f32 v34, v34, v40, v41
	v_bfe_i32 v253, v0, 18, 1
	v_bfi_b32 v42, v253, v44, v123
	v_bfe_i32 v253, v0, 19, 1
	v_bfi_b32 v36, v253, v45, v123
	v_max3_f32 v34, v34, v42, v36
	v_bfe_i32 v253, v0, 24, 1
	v_bfi_b32 v37, v253, v46, v123
	s_nop 1
	v_bfe_i32 v253, v0, 25, 1
	v_bfi_b32 v38, v253, v47, v123
	v_max3_f32 v35, v34, v37, v38
	v_and_b32_e32 v34, 0x4000000, v0
	v_cmp_ne_u32_e32 vcc, 0, v34
	v_and_b32_e32 v0, 0x8000000, v0
	s_nop 0
	v_cndmask_b32_e32 v34, v123, v48, vcc
	s_nop 1
	v_bfe_i32 v253, v0, 27, 1
	v_bfi_b32 v0, v253, v49, v123
	v_max3_f32 v35, v35, v34, v0
	v_mov_b32_e32 v43, v35
	s_nop 1
	v_permlane32_swap_b32_e32 v35, v43
	v_max_f32_e32 v43, v43, v43
	v_max_f32_e32 v35, v35, v35
	v_max_f32_e32 v35, v35, v43
	v_mul_f32_e32 v35, 0x3e38aa3b, v35
	v_add_f32_e32 v43, 0x40c00000, v124
	v_cmp_gt_f32_e32 vcc, v35, v43
	s_cbranch_vccz .LBB0_2624
	v_max_f32_e64 v35, -v35, -v35
	v_max_f32_e64 v43, -v124, -v124
	v_min_f32_e32 v35, v43, v35
	v_add_f32_e32 v43, v124, v35
	v_exp_f32_e32 v44, v43
	s_nop 0
	v_mul_f32_e32 v125, v125, v44
	v_pk_mul_f32 v[32:33], v[32:33], v[44:45] op_sel_hi:[1,0]
	v_pk_mul_f32 v[30:31], v[30:31], v[44:45] op_sel_hi:[1,0]
	v_pk_mul_f32 v[28:29], v[28:29], v[44:45] op_sel_hi:[1,0]
	v_pk_mul_f32 v[26:27], v[26:27], v[44:45] op_sel_hi:[1,0]
	v_pk_mul_f32 v[24:25], v[24:25], v[44:45] op_sel_hi:[1,0]
	v_pk_mul_f32 v[22:23], v[22:23], v[44:45] op_sel_hi:[1,0]
	v_pk_mul_f32 v[20:21], v[20:21], v[44:45] op_sel_hi:[1,0]
	v_pk_mul_f32 v[18:19], v[18:19], v[44:45] op_sel_hi:[1,0]
	v_pk_mul_f32 v[16:17], v[16:17], v[44:45] op_sel_hi:[1,0]
	v_pk_mul_f32 v[14:15], v[14:15], v[44:45] op_sel_hi:[1,0]
	v_pk_mul_f32 v[12:13], v[12:13], v[44:45] op_sel_hi:[1,0]
	v_pk_mul_f32 v[10:11], v[10:11], v[44:45] op_sel_hi:[1,0]
	v_pk_mul_f32 v[8:9], v[8:9], v[44:45] op_sel_hi:[1,0]
	v_pk_mul_f32 v[6:7], v[6:7], v[44:45] op_sel_hi:[1,0]
	v_pk_mul_f32 v[4:5], v[4:5], v[44:45] op_sel_hi:[1,0]
	v_pk_mul_f32 v[2:3], v[2:3], v[44:45] op_sel_hi:[1,0]

; DI float fexp2(float x) { return __builtin_amdgcn_exp2f(x); }
; DI f32x16 mfma32(bf16x8 a, bf16x8 b, f32x16 c) { return __builtin_amdgcn_mfma_f32_32x32x16_bf16(a, b, c, 0, 0, 0); }
; DI float half_max(float v) { auto rr = __builtin_amdgcn_permlane32_swap(__float_as_uint(v), __float_as_uint(v), false, false); return fmaxf(__uint_as_float(rr[0]), __uint_as_float(rr[1])); }
; template <int DVB, bool MASKED = true>
; DI void attn_step32(const bf16* Kt, int KP, const bf16* Vt, int VP, const bf16x8 (&qf)[4], f32x16 (&o)[DVB], float& m, float& l, unsigned vmask, float c2, int lane) {
;   const int r32 = lane & 31, h = lane >> 5;
;   f32x16 s;
; #pragma unroll
;   for (int i = 0; i < 16; ++i) s[i] = 0.f;
; #pragma unroll
;   for (int t = 0; t < 4; ++t) { const bf16x8 kf = *(const bf16x8*)(Kt + r32 * KP + t * 16 + h * 8); s = mfma32(kf, qf[t], s); }
;   float mx = -INFINITY;
; #pragma unroll
;   for (int i = 0; i < 16; ++i) { if (MASKED) { s[i] = ((vmask >> i) & 1u) ? s[i] : -INFINITY; } mx = fmaxf(mx, s[i]); }
;   mx = half_max(mx);
;   const float mxs = mx * c2;
;   if (__any(mxs > m + 6.f)) {
;     const float mn = fmaxf(m, mxs);
;     const float alpha = fexp2(m - mn); l *= alpha;
; #pragma unroll
;     for (int d = 0; d < DVB; ++d)
; #pragma unroll
;       for (int i = 0; i < 16; ++i) o[d][i] *= alpha;
;     m = mn;
;   }
; DI void band_load(KVRegs& R, const bf16* Kg, const bf16* Vg, int NP, int kstart, int dil, int roff, int lane) {
; #pragma unroll
;   for (int i = 0; i < 4; ++i) {
;     const int row = (lane >> 3) + 8 * i, ch = lane & 7; int k = kstart + row; if (k < 0) k = 0;
;     const size_t off = (size_t)(dil * k + roff) * NP + ch * 8;
;     R.k[i] = *(const u32x4*)(Kg + off); R.v[i] = *(const u32x4*)(Vg + off);
;   }
.LBB0_2620:
	v_max_i32_e32 v0, 0, v132
	v_lshl_or_b32 v0, v0, 4, v125
	v_lshlrev_b64 v[34:35], 13, v[0:1]
	s_waitcnt lgkmcnt(0)
	s_waitcnt vmcnt(7)
	ds_write_b128 v113, v[66:69]
	s_waitcnt vmcnt(6)
	ds_write_b128 v113, v[70:73] offset:4608
	s_waitcnt vmcnt(5)
	ds_write_b128 v113, v[74:77] offset:1152
	s_waitcnt vmcnt(4)
	ds_write_b128 v113, v[78:81] offset:5760
	s_waitcnt vmcnt(3)
	ds_write_b128 v113, v[82:85] offset:2304
	s_waitcnt vmcnt(2)
	ds_write_b128 v113, v[86:89] offset:6912
	s_waitcnt vmcnt(1)
	ds_write_b128 v113, v[94:97] offset:3456
	s_waitcnt vmcnt(0)
	ds_write_b128 v113, v[90:93] offset:8064
	v_or_b32_e32 v34, v34, v122
	s_waitcnt lgkmcnt(0)
	v_lshl_add_u64 v[38:39], v[110:111], 0, v[34:35]
	ds_read_b128 v[34:37], v114
	ds_read_b128 v[200:203], v114 offset:32
	ds_read_b128 v[204:207], v114 offset:64
	ds_read_b128 v[208:211], v114 offset:96
	v_max_i32_e32 v0, -8, v132
	v_lshl_add_u32 v0, v0, 4, v133
	global_load_dwordx4 v[66:69], v[38:39], off offset:1024
	global_load_dwordx4 v[70:73], v[38:39], off offset:2048
	v_lshlrev_b64 v[38:39], 13, v[0:1]
	v_or_b32_e32 v38, v38, v122
	v_lshl_add_u64 v[86:87], v[110:111], 0, v[38:39]
	s_waitcnt lgkmcnt(3)
	v_mfma_f32_32x32x16_bf16 v[34:49], v[34:37], v[62:65], 0
	global_load_dwordx4 v[74:77], v[86:87], off offset:1024
	global_load_dwordx4 v[78:81], v[86:87], off offset:2048
	v_max_i32_e32 v0, -16, v132
	v_lshl_add_u32 v0, v0, 4, v134
	v_lshlrev_b64 v[86:87], 13, v[0:1]
	v_max_i32_e32 v0, 0xffffffe8, v132
	v_lshl_add_u32 v0, v0, 4, v135
	s_waitcnt lgkmcnt(2)
	v_mfma_f32_32x32x16_bf16 v[34:49], v[200:203], v[58:61], v[34:49]
	v_lshlrev_b64 v[94:95], 13, v[0:1]
	v_or_b32_e32 v86, v86, v122
	v_or_b32_e32 v94, v94, v122
	v_lshl_add_u64 v[86:87], v[110:111], 0, v[86:87]
	v_lshl_add_u64 v[140:141], v[110:111], 0, v[94:95]
	global_load_dwordx4 v[82:85], v[86:87], off offset:1024
	s_nop 0
	global_load_dwordx4 v[86:89], v[86:87], off offset:2048
	s_waitcnt lgkmcnt(1)
	v_mfma_f32_32x32x16_bf16 v[34:49], v[204:207], v[54:57], v[34:49]
	global_load_dwordx4 v[94:97], v[140:141], off offset:1024
	global_load_dwordx4 v[90:93], v[140:141], off offset:2048
	v_add_u32_e32 v0, s15, v129
	v_max_i32_e32 v140, 0, v0
	v_lshlrev_b32_e64 v140, v140, -1
	v_cmp_gt_i32_e32 vcc, 32, v0
	s_waitcnt lgkmcnt(0)
	v_mfma_f32_32x32x16_bf16 v[34:49], v[208:211], v[50:53], v[34:49]
	v_cndmask_b32_e32 v0, 0, v140, vcc
	v_lshrrev_b32_e32 v140, v98, v0
	s_nop 0
	s_nop 0
	s_nop 0
	s_nop 6
	v_bfe_i32 v253, v140, 0, 1
	v_bfi_b32 v34, v253, v34, v123
	v_bfe_i32 v253, v140, 1, 1
	v_bfi_b32 v35, v253, v35, v123
	v_max3_f32 v137, v34, s2, v35
	v_bfe_i32 v253, v140, 2, 1
	v_bfi_b32 v136, v253, v36, v123
	v_bfe_i32 v253, v140, 3, 1
	v_bfi_b32 v0, v253, v37, v123
	v_max3_f32 v137, v137, v136, v0
	v_bfe_i32 v253, v140, 8, 1
	v_bfi_b32 v36, v253, v38, v123
	v_bfe_i32 v253, v140, 9, 1
	v_bfi_b32 v37, v253, v39, v123
	v_max3_f32 v137, v137, v36, v37
	v_bfe_i32 v253, v140, 10, 1
	v_bfi_b32 v38, v253, v40, v123
	v_bfe_i32 v253, v140, 11, 1
	v_bfi_b32 v39, v253, v41, v123
	v_max3_f32 v137, v137, v38, v39
	v_bfe_i32 v253, v140, 16, 1
	v_bfi_b32 v40, v253, v42, v123
	v_bfe_i32 v253, v140, 17, 1
	v_bfi_b32 v41, v253, v43, v123
	v_max3_f32 v137, v137, v40, v41
	v_bfe_i32 v253, v140, 18, 1
	v_bfi_b32 v42, v253, v44, v123
	v_bfe_i32 v253, v140, 19, 1
	v_bfi_b32 v43, v253, v45, v123
	v_max3_f32 v137, v137, v42, v43
	v_bfe_i32 v253, v140, 24, 1
	v_bfi_b32 v44, v253, v46, v123
	v_bfe_i32 v253, v140, 25, 1
	v_bfi_b32 v45, v253, v47, v123
	v_max3_f32 v137, v137, v44, v45
	v_bfe_i32 v253, v140, 26, 1
	v_bfi_b32 v46, v253, v48, v123
	s_nop 1
	v_bfe_i32 v253, v140, 27, 1
	v_bfi_b32 v47, v253, v49, v123
	v_max3_f32 v48, v137, v46, v47
	v_mov_b32_e32 v49, v48
	s_nop 1
	v_permlane32_swap_b32_e32 v48, v49
	v_max_f32_e32 v49, v49, v49
	v_max_f32_e32 v48, v48, v48
	v_max_f32_e32 v48, v48, v49
	v_mul_f32_e32 v48, 0x3e38aa3b, v48
	v_add_f32_e32 v49, 0x40c00000, v124
	v_cmp_gt_f32_e32 vcc, v48, v49
	s_cbranch_vccz .LBB0_2619
	v_max_f32_e32 v48, v48, v48
	v_max_f32_e32 v49, v124, v124
	v_max_f32_e32 v49, v49, v48
	v_sub_f32_e32 v48, v124, v49
	v_exp_f32_e32 v48, v48
	v_mov_b32_e32 v124, v49
	v_mul_f32_e32 v130, v130, v48
	v_pk_mul_f32 v[32:33], v[32:33], v[48:49] op_sel_hi:[1,0]
	v_pk_mul_f32 v[30:31], v[30:31], v[48:49] op_sel_hi:[1,0]
	v_pk_mul_f32 v[28:29], v[28:29], v[48:49] op_sel_hi:[1,0]
	v_pk_mul_f32 v[26:27], v[26:27], v[48:49] op_sel_hi:[1,0]
	v_pk_mul_f32 v[24:25], v[24:25], v[48:49] op_sel_hi:[1,0]
	v_pk_mul_f32 v[22:23], v[22:23], v[48:49] op_sel_hi:[1,0]
	v_pk_mul_f32 v[20:21], v[20:21], v[48:49] op_sel_hi:[1,0]
	v_pk_mul_f32 v[18:19], v[18:19], v[48:49] op_sel_hi:[1,0]
	v_pk_mul_f32 v[16:17], v[16:17], v[48:49] op_sel_hi:[1,0]
	v_pk_mul_f32 v[14:15], v[14:15], v[48:49] op_sel_hi:[1,0]
	v_pk_mul_f32 v[12:13], v[12:13], v[48:49] op_sel_hi:[1,0]
	v_pk_mul_f32 v[10:11], v[10:11], v[48:49] op_sel_hi:[1,0]
	v_pk_mul_f32 v[8:9], v[8:9], v[48:49] op_sel_hi:[1,0]
	v_pk_mul_f32 v[6:7], v[6:7], v[48:49] op_sel_hi:[1,0]
	v_pk_mul_f32 v[4:5], v[4:5], v[48:49] op_sel_hi:[1,0]
	v_pk_mul_f32 v[2:3], v[2:3], v[48:49] op_sel_hi:[1,0]
	s_branch .LBB0_2619
; DI float fexp2(float x) { return __builtin_amdgcn_exp2f(x); }
; DI f32x16 mfma32(bf16x8 a, bf16x8 b, f32x16 c) { return __builtin_amdgcn_mfma_f32_32x32x16_bf16(a, b, c, 0, 0, 0); }
; DI float half_max(float v) { auto rr = __builtin_amdgcn_permlane32_swap(__float_as_uint(v), __float_as_uint(v), false, false); return fmaxf(__uint_as_float(rr[0]), __uint_as_float(rr[1])); }
; template <int DVB, bool MASKED = true>
; DI void attn_step32(const bf16* Kt, int KP, const bf16* Vt, int VP, const bf16x8 (&qf)[4], f32x16 (&o)[DVB], float& m, float& l, unsigned vmask, float c2, int lane) {
;   const int r32 = lane & 31, h = lane >> 5;
;   f32x16 s;
; #pragma unroll
;   for (int i = 0; i < 16; ++i) s[i] = 0.f;
; #pragma unroll
;   for (int t = 0; t < 4; ++t) { const bf16x8 kf = *(const bf16x8*)(Kt + r32 * KP + t * 16 + h * 8); s = mfma32(kf, qf[t], s); }
;   float mx = -INFINITY;
; #pragma unroll
;   for (int i = 0; i < 16; ++i) { if (MASKED) { s[i] = ((vmask >> i) & 1u) ? s[i] : -INFINITY; } mx = fmaxf(mx, s[i]); }
;   mx = half_max(mx);
;   const float mxs = mx * c2;
;   if (__any(mxs > m + 6.f)) {
;     const float mn = fmaxf(m, mxs);
;     const float alpha = fexp2(m - mn); l *= alpha;
; #pragma unroll
;     for (int d = 0; d < DVB; ++d)
; #pragma unroll
;       for (int i = 0; i < 16; ++i) o[d][i] *= alpha;
;     m = mn;
;   }
; DI unsigned row_range_mask(int lo, int hi) {
;   lo = lo < 0 ? 0 : lo; hi = hi > 31 ? 31 : hi;
;   if (hi < lo) return 0u;
;   const unsigned upto_hi = (hi >= 31) ? 0xffffffffu : ((1u << (hi + 1)) - 1u);
;   return upto_hi & ~((1u << lo) - 1u);
; }
; DI unsigned lane_rows(unsigned m32, int h) {
;   const unsigned t = m32 >> (4 * h);
;   return (t & 0xFu) | ((t >> 4) & 0xF0u) | ((t >> 8) & 0xF00u) | ((t >> 12) & 0xF000u);
; }
.LBB0_2622:
	s_waitcnt lgkmcnt(0)
	s_waitcnt vmcnt(7)
	ds_write_b128 v113, v[66:69]
	s_waitcnt vmcnt(6)
	ds_write_b128 v113, v[70:73] offset:4608
	s_waitcnt vmcnt(5)
	ds_write_b128 v113, v[74:77] offset:1152
	s_waitcnt vmcnt(4)
	ds_write_b128 v113, v[78:81] offset:5760
	s_waitcnt vmcnt(3)
	ds_write_b128 v113, v[82:85] offset:2304
	s_waitcnt vmcnt(2)
	ds_write_b128 v113, v[86:89] offset:6912
	s_waitcnt vmcnt(1)
	ds_write_b128 v113, v[94:97] offset:3456
	s_waitcnt vmcnt(0)
	ds_write_b128 v113, v[90:93] offset:8064
	s_waitcnt lgkmcnt(0)
	ds_read_b128 v[34:37], v114
	ds_read_b128 v[66:69], v114 offset:32
	ds_read_b128 v[70:73], v114 offset:64
	s_waitcnt lgkmcnt(2)
	v_mfma_f32_32x32x16_bf16 v[34:49], v[34:37], v[62:65], 0
	v_sub_u32_e32 v74, v128, v126
	v_min_i32_e32 v75, 31, v74
	v_sub_u32_e64 v0, v128, s1 clamp
	v_add_u32_e32 v76, 1, v75
	v_sub_u32_e32 v0, v0, v126
	v_max_i32_e32 v0, 0, v0
	v_cmp_gt_u32_e32 vcc, 31, v74
	s_waitcnt lgkmcnt(1)
	v_mfma_f32_32x32x16_bf16 v[34:49], v[66:69], v[58:61], v[34:49]
	v_lshlrev_b32_e64 v66, v76, -1
	v_not_b32_e32 v66, v66
	v_cndmask_b32_e32 v66, -1, v66, vcc
	v_lshlrev_b32_e64 v67, v0, -1
	v_and_b32_e32 v74, v66, v67
	ds_read_b128 v[66:69], v114 offset:96
	v_cmp_ge_i32_e32 vcc, v75, v0
	s_waitcnt lgkmcnt(1)
	v_mfma_f32_32x32x16_bf16 v[34:49], v[70:73], v[54:57], v[34:49]
	v_cndmask_b32_e32 v0, 0, v74, vcc
	v_lshrrev_b32_e32 v0, v98, v0
	s_nop 0
	s_nop 0
	s_nop 0
	s_nop 0
	s_waitcnt lgkmcnt(0)
	v_mfma_f32_32x32x16_bf16 v[34:49], v[66:69], v[50:53], v[34:49]
	s_nop 0
	s_nop 10
	v_bfe_i32 v253, v0, 0, 1
	v_bfi_b32 v135, v253, v34, v123
	s_nop 0
	s_nop 1
	v_bfe_i32 v253, v0, 1, 1
	v_bfi_b32 v136, v253, v35, v123
	v_max3_f32 v35, v135, s2, v136
	s_nop 0
	v_bfe_i32 v253, v0, 2, 1
	v_bfi_b32 v36, v253, v36, v123
	s_nop 0
	s_nop 1
	v_bfe_i32 v253, v0, 3, 1
	v_bfi_b32 v34, v253, v37, v123
	v_max3_f32 v66, v35, v36, v34
	s_nop 0
	v_bfe_i32 v253, v0, 8, 1
	v_bfi_b32 v35, v253, v38, v123
	v_bfe_i32 v253, v0, 9, 1
	v_bfi_b32 v37, v253, v39, v123
	v_max3_f32 v66, v66, v35, v37
	v_bfe_i32 v253, v0, 10, 1
	v_bfi_b32 v38, v253, v40, v123
	v_bfe_i32 v253, v0, 11, 1
	v_bfi_b32 v39, v253, v41, v123
	v_max3_f32 v66, v66, v38, v39
	v_bfe_i32 v253, v0, 16, 1
	v_bfi_b32 v40, v253, v42, v123
	v_bfe_i32 v253, v0, 17, 1
	v_bfi_b32 v41, v253, v43, v123
	v_max3_f32 v66, v66, v40, v41
	v_bfe_i32 v253, v0, 18, 1
	v_bfi_b32 v42, v253, v44, v123
	v_bfe_i32 v253, v0, 19, 1
	v_bfi_b32 v43, v253, v45, v123
	v_and_b32_e32 v45, 0x2000000, v0
	v_max3_f32 v66, v66, v42, v43
	v_bfe_i32 v253, v0, 24, 1
	v_bfi_b32 v44, v253, v46, v123
	v_cmp_ne_u32_e32 vcc, 0, v45
	v_and_b32_e32 v46, 0x4000000, v0
	v_and_b32_e32 v0, 0x8000000, v0
	v_cndmask_b32_e32 v45, v123, v47, vcc
	v_cmp_ne_u32_e32 vcc, 0, v46
	v_max3_f32 v66, v66, v44, v45
	s_nop 0
	v_cndmask_b32_e32 v46, v123, v48, vcc
	s_nop 1
	v_bfe_i32 v253, v0, 27, 1
	v_bfi_b32 v47, v253, v49, v123
	v_max3_f32 v0, v66, v46, v47
	v_mov_b32_e32 v48, v0
	s_nop 1
	v_permlane32_swap_b32_e32 v0, v48
	v_max_f32_e32 v48, v48, v48
	v_max_f32_e32 v0, v0, v0
	v_max_f32_e32 v0, v0, v48
	v_mul_f32_e32 v0, 0x3e38aa3b, v0
	v_add_f32_e32 v48, 0x40c00000, v124
	v_cmp_gt_f32_e32 vcc, v0, v48
	s_cbranch_vccz .LBB0_2625
	v_max_f32_e32 v0, v0, v0
	v_max_f32_e32 v48, v124, v124
	v_max_f32_e32 v49, v48, v0
	v_sub_f32_e32 v0, v124, v49
	v_exp_f32_e32 v0, v0
	v_xor_b32_e32 v48, 0x80000000, v49
	v_mov_b32_e32 v124, v49
	v_mul_f32_e32 v130, v130, v0
	v_pk_mul_f32 v[32:33], v[32:33], v[0:1] op_sel_hi:[1,0]
	v_pk_mul_f32 v[30:31], v[30:31], v[0:1] op_sel_hi:[1,0]
	v_pk_mul_f32 v[28:29], v[28:29], v[0:1] op_sel_hi:[1,0]
	v_pk_mul_f32 v[26:27], v[26:27], v[0:1] op_sel_hi:[1,0]
	v_pk_mul_f32 v[24:25], v[24:25], v[0:1] op_sel_hi:[1,0]
	v_pk_mul_f32 v[22:23], v[22:23], v[0:1] op_sel_hi:[1,0]
	v_pk_mul_f32 v[20:21], v[20:21], v[0:1] op_sel_hi:[1,0]
	v_pk_mul_f32 v[18:19], v[18:19], v[0:1] op_sel_hi:[1,0]
	v_pk_mul_f32 v[16:17], v[16:17], v[0:1] op_sel_hi:[1,0]
	v_pk_mul_f32 v[14:15], v[14:15], v[0:1] op_sel_hi:[1,0]
	v_pk_mul_f32 v[12:13], v[12:13], v[0:1] op_sel_hi:[1,0]
	v_pk_mul_f32 v[10:11], v[10:11], v[0:1] op_sel_hi:[1,0]
	v_pk_mul_f32 v[8:9], v[8:9], v[0:1] op_sel_hi:[1,0]
	v_pk_mul_f32 v[6:7], v[6:7], v[0:1] op_sel_hi:[1,0]
	v_pk_mul_f32 v[4:5], v[4:5], v[0:1] op_sel_hi:[1,0]
	v_pk_mul_f32 v[2:3], v[2:3], v[0:1] op_sel_hi:[1,0]
	s_branch .LBB0_2626

; template <int DVB, bool MASKED = true>
; DI void attn_step32(const bf16* Kt, int KP, const bf16* Vt, int VP, const bf16x8 (&qf)[4], f32x16 (&o)[DVB], float& m, float& l, unsigned vmask, float c2, int lane) {
;   const int r32 = lane & 31, h = lane >> 5;
;   f32x16 s;
; #pragma unroll
;   for (int i = 0; i < 16; ++i) s[i] = 0.f;
; #pragma unroll
;   for (int t = 0; t < 4; ++t) { const bf16x8 kf = *(const bf16x8*)(Kt + r32 * KP + t * 16 + h * 8); s = mfma32(kf, qf[t], s); }
;   float mx = -INFINITY;
; #pragma unroll
;   for (int i = 0; i < 16; ++i) { if (MASKED) { s[i] = ((vmask >> i) & 1u) ? s[i] : -INFINITY; } mx = fmaxf(mx, s[i]); }
;   mx = half_max(mx);
;   const float mxs = mx * c2;
;   if (__any(mxs > m + 6.f)) {
;     const float mn = fmaxf(m, mxs);
;     const float alpha = fexp2(m - mn); l *= alpha;
; #pragma unroll
;     for (int d = 0; d < DVB; ++d)
; #pragma unroll
;       for (int i = 0; i < 16; ++i) o[d][i] *= alpha;
;     m = mn;
;   }
; DI void kv_store(const KVRegs& R, bf16* Ks, bf16* Vs, int lane) {
; #pragma unroll
;   for (int i = 0; i < 4; ++i) { const int row = (lane >> 3) + 8 * i, ch = lane & 7; *(u32x4*)(Ks + row * WP + ch * 8) = R.k[i]; *(u32x4*)(Vs + row * WP + ch * 8) = R.v[i]; }
; }
; DI void band_load(KVRegs& R, const bf16* Kg, const bf16* Vg, int NP, int kstart, int dil, int roff, int lane) {
; #pragma unroll
;   for (int i = 0; i < 4; ++i) {
;     const int row = (lane >> 3) + 8 * i, ch = lane & 7; int k = kstart + row; if (k < 0) k = 0;
;     const size_t off = (size_t)(dil * k + roff) * NP + ch * 8;
;     R.k[i] = *(const u32x4*)(Kg + off); R.v[i] = *(const u32x4*)(Vg + off);
;   }
; }
; template <int DVB>
; DI void band_run(const bf16* Kg, const bf16* Vg, int NP, int kbase, int nsteps, int dil, int roff, int qidx, int win,
;                  const bf16x8 (&qf)[4], f32x16 (&o)[DVB], float& m, float& l, float c2, bf16* Ks, bf16* Vs, int lane) {
;   const int h = lane >> 5;
;   KVRegs R; band_load(R, Kg, Vg, NP, kbase, dil, roff, lane);
;   for (int j = 0; j < nsteps; ++j) {
;     lds_fence();
;     kv_store(R, Ks, Vs, lane);
;     lds_fence();
;     if (j + 1 < nsteps) band_load(R, Kg, Vg, NP, kbase + 32 * (j + 1), dil, roff, lane);
;     const int kb = kbase + 32 * j, lo_r = (qidx - win > 0 ? qidx - win : 0) - kb;
;     const unsigned vm = lane_rows(row_range_mask(lo_r, qidx - kb), h);
.LBB0_2628:
	v_max_i32_e32 v0, 0, v135
	v_lshl_or_b32 v0, v0, 2, v133
	v_lshlrev_b64 v[34:35], 13, v[0:1]
	v_or_b32_e32 v34, v34, v122
	v_max_i32_e32 v0, -8, v135
	s_waitcnt lgkmcnt(0)
	s_waitcnt vmcnt(7)
	ds_write_b128 v113, v[66:69]
	s_waitcnt vmcnt(6)
	ds_write_b128 v113, v[70:73] offset:4608
	s_waitcnt vmcnt(5)
	ds_write_b128 v113, v[74:77] offset:1152
	s_waitcnt vmcnt(4)
	ds_write_b128 v113, v[78:81] offset:5760
	s_waitcnt vmcnt(3)
	ds_write_b128 v113, v[82:85] offset:2304
	s_waitcnt vmcnt(2)
	ds_write_b128 v113, v[86:89] offset:6912
	s_waitcnt vmcnt(1)
	ds_write_b128 v113, v[94:97] offset:3456
	s_waitcnt vmcnt(0)
	ds_write_b128 v113, v[90:93] offset:8064
	v_lshl_add_u64 v[34:35], v[110:111], 0, v[34:35]
	v_lshl_add_u32 v0, v0, 2, v136
	s_waitcnt lgkmcnt(0)
	global_load_dwordx4 v[66:69], v[34:35], off offset:1024
	global_load_dwordx4 v[70:73], v[34:35], off offset:2048
	v_lshlrev_b64 v[34:35], 13, v[0:1]
	v_max_i32_e32 v0, -16, v135
	v_lshl_add_u32 v0, v0, 2, v137
	v_lshlrev_b64 v[38:39], 13, v[0:1]
	v_max_i32_e32 v0, 0xffffffe8, v135
	v_lshl_add_u32 v0, v0, 2, v138
	v_lshlrev_b64 v[90:91], 13, v[0:1]
	v_or_b32_e32 v34, v34, v122
	v_or_b32_e32 v38, v38, v122
	v_or_b32_e32 v90, v90, v122
	v_lshl_add_u64 v[34:35], v[110:111], 0, v[34:35]
	v_lshl_add_u64 v[38:39], v[110:111], 0, v[38:39]
	v_lshl_add_u64 v[90:91], v[110:111], 0, v[90:91]
	global_load_dwordx4 v[74:77], v[34:35], off offset:1024
	global_load_dwordx4 v[78:81], v[34:35], off offset:2048
	ds_read_b128 v[34:37], v114
	ds_read_b128 v[200:203], v114 offset:32
	ds_read_b128 v[204:207], v114 offset:64
	ds_read_b128 v[208:211], v114 offset:96
	global_load_dwordx4 v[82:85], v[38:39], off offset:1024
	global_load_dwordx4 v[86:89], v[38:39], off offset:2048
	global_load_dwordx4 v[94:97], v[90:91], off offset:1024
	s_nop 0
	global_load_dwordx4 v[90:93], v[90:91], off offset:2048
	s_waitcnt lgkmcnt(3)
	v_mfma_f32_32x32x16_bf16 v[34:49], v[34:37], v[62:65], 0
	v_add_u32_e32 v139, s15, v119
	v_min_i32_e32 v148, 31, v139
	v_add_u32_e32 v0, s15, v134
	v_max_i32_e32 v0, 0, v0
	v_cmp_gt_i32_e32 vcc, 31, v139
	s_waitcnt lgkmcnt(2)
	v_mfma_f32_32x32x16_bf16 v[34:49], v[200:203], v[58:61], v[34:49]
	v_add_u32_e32 v140, 1, v148
	v_lshlrev_b32_e64 v140, v140, -1
	v_not_b32_e32 v149, v140
	v_cndmask_b32_e32 v139, -1, v149, vcc
	v_cmp_ge_i32_e32 vcc, v148, v0
	s_waitcnt lgkmcnt(1)
	v_mfma_f32_32x32x16_bf16 v[34:49], v[204:207], v[54:57], v[34:49]
	v_lshlrev_b32_e64 v144, v0, -1
	v_and_b32_e32 v139, v139, v144
	v_cndmask_b32_e32 v0, 0, v139, vcc
	v_lshrrev_b32_e32 v144, v98, v0
	s_nop 0
	s_nop 0
	s_nop 0
	s_waitcnt lgkmcnt(0)
	v_mfma_f32_32x32x16_bf16 v[34:49], v[208:211], v[50:53], v[34:49]
	s_nop 11
	v_bfe_i32 v253, v144, 0, 1
	v_bfi_b32 v34, v253, v34, v123
	v_bfe_i32 v253, v144, 1, 1
	v_bfi_b32 v35, v253, v35, v123
	v_max3_f32 v140, v34, s2, v35
	v_bfe_i32 v253, v144, 2, 1
	v_bfi_b32 v139, v253, v36, v123
	v_bfe_i32 v253, v144, 3, 1
	v_bfi_b32 v0, v253, v37, v123
	v_max3_f32 v140, v140, v139, v0
	v_bfe_i32 v253, v144, 8, 1
	v_bfi_b32 v36, v253, v38, v123
	v_bfe_i32 v253, v144, 9, 1
	v_bfi_b32 v37, v253, v39, v123
	v_max3_f32 v140, v140, v36, v37
	v_bfe_i32 v253, v144, 10, 1
	v_bfi_b32 v38, v253, v40, v123
	v_bfe_i32 v253, v144, 11, 1
	v_bfi_b32 v39, v253, v41, v123
	v_max3_f32 v140, v140, v38, v39
	v_bfe_i32 v253, v144, 16, 1
	v_bfi_b32 v40, v253, v42, v123
	v_bfe_i32 v253, v144, 17, 1
	v_bfi_b32 v41, v253, v43, v123
	v_max3_f32 v140, v140, v40, v41
	v_bfe_i32 v253, v144, 18, 1
	v_bfi_b32 v42, v253, v44, v123
	v_bfe_i32 v253, v144, 19, 1
	v_bfi_b32 v43, v253, v45, v123
	v_max3_f32 v140, v140, v42, v43
	v_bfe_i32 v253, v144, 24, 1
	v_bfi_b32 v44, v253, v46, v123
	v_bfe_i32 v253, v144, 25, 1
	v_bfi_b32 v45, v253, v47, v123
	v_max3_f32 v140, v140, v44, v45
	v_bfe_i32 v253, v144, 26, 1
	v_bfi_b32 v46, v253, v48, v123
	s_nop 1
	v_bfe_i32 v253, v144, 27, 1
	v_bfi_b32 v47, v253, v49, v123
	v_max3_f32 v48, v140, v46, v47
	v_mov_b32_e32 v49, v48
	s_nop 1
	v_permlane32_swap_b32_e32 v48, v49
	v_max_f32_e32 v49, v49, v49
	v_max_f32_e32 v48, v48, v48
	v_max_f32_e32 v48, v48, v49
	v_mul_f32_e32 v48, 0x3e38aa3b, v48
	v_add_f32_e32 v49, 0x40c00000, v124
	v_cmp_gt_f32_e32 vcc, v48, v49
	s_cbranch_vccz .LBB0_2627
	v_max_f32_e32 v48, v48, v48
	v_max_f32_e32 v49, v124, v124
	v_max_f32_e32 v49, v49, v48
	v_sub_f32_e32 v48, v124, v49
	v_exp_f32_e32 v48, v48
	v_mov_b32_e32 v124, v49
	v_mul_f32_e32 v130, v130, v48
	v_pk_mul_f32 v[32:33], v[32:33], v[48:49] op_sel_hi:[1,0]
	v_pk_mul_f32 v[30:31], v[30:31], v[48:49] op_sel_hi:[1,0]
	v_pk_mul_f32 v[28:29], v[28:29], v[48:49] op_sel_hi:[1,0]
	v_pk_mul_f32 v[26:27], v[26:27], v[48:49] op_sel_hi:[1,0]
	v_pk_mul_f32 v[24:25], v[24:25], v[48:49] op_sel_hi:[1,0]
	v_pk_mul_f32 v[22:23], v[22:23], v[48:49] op_sel_hi:[1,0]
	v_pk_mul_f32 v[20:21], v[20:21], v[48:49] op_sel_hi:[1,0]
	v_pk_mul_f32 v[18:19], v[18:19], v[48:49] op_sel_hi:[1,0]
	v_pk_mul_f32 v[16:17], v[16:17], v[48:49] op_sel_hi:[1,0]
	v_pk_mul_f32 v[14:15], v[14:15], v[48:49] op_sel_hi:[1,0]
	v_pk_mul_f32 v[12:13], v[12:13], v[48:49] op_sel_hi:[1,0]
	v_pk_mul_f32 v[10:11], v[10:11], v[48:49] op_sel_hi:[1,0]
	v_pk_mul_f32 v[8:9], v[8:9], v[48:49] op_sel_hi:[1,0]
	v_pk_mul_f32 v[6:7], v[6:7], v[48:49] op_sel_hi:[1,0]
	v_pk_mul_f32 v[4:5], v[4:5], v[48:49] op_sel_hi:[1,0]
	v_pk_mul_f32 v[2:3], v[2:3], v[48:49] op_sel_hi:[1,0]
	s_branch .LBB0_2627
; DI float fexp2(float x) { return __builtin_amdgcn_exp2f(x); }
; DI f32x16 mfma32(bf16x8 a, bf16x8 b, f32x16 c) { return __builtin_amdgcn_mfma_f32_32x32x16_bf16(a, b, c, 0, 0, 0); }
; DI void lds_fence() { asm volatile("s_waitcnt lgkmcnt(0)" ::: "memory"); __builtin_amdgcn_wave_barrier(); }
; DI float half_max(float v) { auto rr = __builtin_amdgcn_permlane32_swap(__float_as_uint(v), __float_as_uint(v), false, false); return fmaxf(__uint_as_float(rr[0]), __uint_as_float(rr[1])); }
; template <int DVB, bool MASKED = true>
; DI void attn_step32(const bf16* Kt, int KP, const bf16* Vt, int VP, const bf16x8 (&qf)[4], f32x16 (&o)[DVB], float& m, float& l, unsigned vmask, float c2, int lane) {
;   const int r32 = lane & 31, h = lane >> 5;
;   f32x16 s;
; #pragma unroll
;   for (int i = 0; i < 16; ++i) s[i] = 0.f;
; #pragma unroll
;   for (int t = 0; t < 4; ++t) { const bf16x8 kf = *(const bf16x8*)(Kt + r32 * KP + t * 16 + h * 8); s = mfma32(kf, qf[t], s); }
;   float mx = -INFINITY;
; #pragma unroll
;   for (int i = 0; i < 16; ++i) { if (MASKED) { s[i] = ((vmask >> i) & 1u) ? s[i] : -INFINITY; } mx = fmaxf(mx, s[i]); }
;   mx = half_max(mx);
;   const float mxs = mx * c2;
;   if (__any(mxs > m + 6.f)) {
;     const float mn = fmaxf(m, mxs);
;     const float alpha = fexp2(m - mn); l *= alpha;
; #pragma unroll
;     for (int d = 0; d < DVB; ++d)
; #pragma unroll
;       for (int i = 0; i < 16; ++i) o[d][i] *= alpha;
;     m = mn;
;   }
; template <int DVB>
; DI void band_run(const bf16* Kg, const bf16* Vg, int NP, int kbase, int nsteps, int dil, int roff, int qidx, int win,
;                  const bf16x8 (&qf)[4], f32x16 (&o)[DVB], float& m, float& l, float c2, bf16* Ks, bf16* Vs, int lane) {
;     ...
;   for (int j = 0; j < nsteps; ++j) {
;     lds_fence();
;     kv_store(R, Ks, Vs, lane);
;     lds_fence();
;     if (j + 1 < nsteps) band_load(R, Kg, Vg, NP, kbase + 32 * (j + 1), dil, roff, lane);
;     const int kb = kbase + 32 * j, lo_r = (qidx - win > 0 ? qidx - win : 0) - kb;
;     const unsigned vm = lane_rows(row_range_mask(lo_r, qidx - kb), h);
;     attn_step32<DVB>(Ks, WP, Vs, WP, qf, o, m, l, vm, c2, lane);
;   }
.LBB0_2630:
	s_waitcnt lgkmcnt(0)
	s_waitcnt vmcnt(7)
	ds_write_b128 v113, v[66:69]
	s_waitcnt vmcnt(6)
	ds_write_b128 v113, v[70:73] offset:4608
	s_waitcnt vmcnt(5)
	ds_write_b128 v113, v[74:77] offset:1152
	s_waitcnt vmcnt(4)
	ds_write_b128 v113, v[78:81] offset:5760
	s_waitcnt vmcnt(3)
	ds_write_b128 v113, v[82:85] offset:2304
	s_waitcnt vmcnt(2)
	ds_write_b128 v113, v[86:89] offset:6912
	s_waitcnt vmcnt(1)
	ds_write_b128 v113, v[94:97] offset:3456
	s_waitcnt vmcnt(0)
	ds_write_b128 v113, v[90:93] offset:8064
	s_waitcnt lgkmcnt(0)
	ds_read_b128 v[34:37], v114
	ds_read_b128 v[66:69], v114 offset:32
	v_lshl_or_b32 v0, v128, 2, v132
	v_max_i32_e32 v70, 0x80, v0
	v_add_u32_e32 v71, 0xe0, v131
	v_sub_u32_e32 v70, v70, v71
	v_add_u32_e32 v70, 0xffffff80, v70
	s_waitcnt lgkmcnt(1)
	v_mfma_f32_32x32x16_bf16 v[34:49], v[34:37], v[62:65], 0
	v_sub_u32_e32 v0, v0, v71
	v_max_i32_e32 v74, 0, v70
	ds_read_b128 v[70:73], v114 offset:64
	v_min_i32_e32 v75, 31, v0
	v_cmp_gt_i32_e32 vcc, 31, v0
	v_lshlrev_b32_e64 v76, v74, -1
	s_waitcnt lgkmcnt(1)
	v_mfma_f32_32x32x16_bf16 v[34:49], v[66:69], v[58:61], v[34:49]
	v_add_u32_e32 v66, 1, v75
	v_lshlrev_b32_e64 v66, v66, -1
	v_not_b32_e32 v66, v66
	v_cndmask_b32_e32 v0, -1, v66, vcc
	ds_read_b128 v[66:69], v114 offset:96
	v_and_b32_e32 v0, v0, v76
	v_cmp_ge_i32_e32 vcc, v75, v74
	s_waitcnt lgkmcnt(1)
	v_mfma_f32_32x32x16_bf16 v[34:49], v[70:73], v[54:57], v[34:49]
	v_cndmask_b32_e32 v0, 0, v0, vcc
	v_lshrrev_b32_e32 v0, v98, v0
	s_nop 0
	s_nop 0
	s_nop 0
	s_nop 0
	s_waitcnt lgkmcnt(0)
	v_mfma_f32_32x32x16_bf16 v[34:49], v[66:69], v[50:53], v[34:49]
	s_nop 11
	v_bfe_i32 v253, v0, 0, 1
	v_bfi_b32 v128, v253, v34, v123
	v_bfe_i32 v253, v0, 1, 1
	v_bfi_b32 v35, v253, v35, v123
	v_max3_f32 v66, v128, s2, v35
	s_nop 0
	v_bfe_i32 v253, v0, 2, 1
	v_bfi_b32 v131, v253, v36, v123
	v_bfe_i32 v253, v0, 3, 1
	v_bfi_b32 v34, v253, v37, v123
	v_max3_f32 v66, v66, v131, v34
	v_bfe_i32 v253, v0, 8, 1
	v_bfi_b32 v36, v253, v38, v123
	v_bfe_i32 v253, v0, 9, 1
	v_bfi_b32 v37, v253, v39, v123
	v_max3_f32 v66, v66, v36, v37
	v_bfe_i32 v253, v0, 10, 1
	v_bfi_b32 v38, v253, v40, v123
	v_bfe_i32 v253, v0, 11, 1
	v_bfi_b32 v39, v253, v41, v123
	v_max3_f32 v66, v66, v38, v39
	v_bfe_i32 v253, v0, 16, 1
	v_bfi_b32 v40, v253, v42, v123
	v_bfe_i32 v253, v0, 17, 1
	v_bfi_b32 v41, v253, v43, v123
	v_max3_f32 v66, v66, v40, v41
	v_bfe_i32 v253, v0, 18, 1
	v_bfi_b32 v42, v253, v44, v123
	v_bfe_i32 v253, v0, 19, 1
	v_bfi_b32 v43, v253, v45, v123
	v_and_b32_e32 v45, 0x2000000, v0
	v_max3_f32 v66, v66, v42, v43
	v_bfe_i32 v253, v0, 24, 1
	v_bfi_b32 v44, v253, v46, v123
	v_cmp_ne_u32_e32 vcc, 0, v45
	v_and_b32_e32 v46, 0x4000000, v0
	v_and_b32_e32 v0, 0x8000000, v0
	v_cndmask_b32_e32 v45, v123, v47, vcc
	v_cmp_ne_u32_e32 vcc, 0, v46
	v_max3_f32 v66, v66, v44, v45
	s_nop 0
	v_cndmask_b32_e32 v46, v123, v48, vcc
	s_nop 1
	v_bfe_i32 v253, v0, 27, 1
	v_bfi_b32 v47, v253, v49, v123
	v_max3_f32 v0, v66, v46, v47
	v_mov_b32_e32 v48, v0
	s_nop 1
	v_permlane32_swap_b32_e32 v0, v48
	v_max_f32_e32 v48, v48, v48
	v_max_f32_e32 v0, v0, v0
	v_max_f32_e32 v0, v0, v48
	v_mul_f32_e32 v0, 0x3e38aa3b, v0
	v_add_f32_e32 v48, 0x40c00000, v124
	v_cmp_gt_f32_e32 vcc, v0, v48
	s_cbranch_vccz .LBB0_2632
	v_max_f32_e32 v0, v0, v0
	v_max_f32_e32 v48, v124, v124
	v_max_f32_e32 v49, v48, v0
	v_sub_f32_e32 v0, v124, v49
	v_exp_f32_e32 v0, v0
	v_xor_b32_e32 v48, 0x80000000, v49
	v_mov_b32_e32 v124, v49
	v_mul_f32_e32 v130, v130, v0
	v_pk_mul_f32 v[32:33], v[32:33], v[0:1] op_sel_hi:[1,0]
	v_pk_mul_f32 v[30:31], v[30:31], v[0:1] op_sel_hi:[1,0]
	v_pk_mul_f32 v[28:29], v[28:29], v[0:1] op_sel_hi:[1,0]
	v_pk_mul_f32 v[26:27], v[26:27], v[0:1] op_sel_hi:[1,0]
	v_pk_mul_f32 v[24:25], v[24:25], v[0:1] op_sel_hi:[1,0]
	v_pk_mul_f32 v[22:23], v[22:23], v[0:1] op_sel_hi:[1,0]
	v_pk_mul_f32 v[20:21], v[20:21], v[0:1] op_sel_hi:[1,0]
	v_pk_mul_f32 v[18:19], v[18:19], v[0:1] op_sel_hi:[1,0]
	v_pk_mul_f32 v[16:17], v[16:17], v[0:1] op_sel_hi:[1,0]
	v_pk_mul_f32 v[14:15], v[14:15], v[0:1] op_sel_hi:[1,0]
	v_pk_mul_f32 v[12:13], v[12:13], v[0:1] op_sel_hi:[1,0]
	v_pk_mul_f32 v[10:11], v[10:11], v[0:1] op_sel_hi:[1,0]
	v_pk_mul_f32 v[8:9], v[8:9], v[0:1] op_sel_hi:[1,0]
	v_pk_mul_f32 v[6:7], v[6:7], v[0:1] op_sel_hi:[1,0]
	v_pk_mul_f32 v[4:5], v[4:5], v[0:1] op_sel_hi:[1,0]
	v_pk_mul_f32 v[2:3], v[2:3], v[0:1] op_sel_hi:[1,0]
	s_branch .LBB0_2633

; template <int DVB, bool MASKED = true>
; DI void attn_step32(const bf16* Kt, int KP, const bf16* Vt, int VP, const bf16x8 (&qf)[4], f32x16 (&o)[DVB], float& m, float& l, unsigned vmask, float c2, int lane) {
;   const int r32 = lane & 31, h = lane >> 5;
;   f32x16 s;
; #pragma unroll
;   for (int i = 0; i < 16; ++i) s[i] = 0.f;
; #pragma unroll
;   for (int t = 0; t < 4; ++t) { const bf16x8 kf = *(const bf16x8*)(Kt + r32 * KP + t * 16 + h * 8); s = mfma32(kf, qf[t], s); }
;   float mx = -INFINITY;
; #pragma unroll
;   for (int i = 0; i < 16; ++i) { if (MASKED) { s[i] = ((vmask >> i) & 1u) ? s[i] : -INFINITY; } mx = fmaxf(mx, s[i]); }
;   mx = half_max(mx);
;   const float mxs = mx * c2;
;   if (__any(mxs > m + 6.f)) {
;     const float mn = fmaxf(m, mxs);
;     const float alpha = fexp2(m - mn); l *= alpha;
; #pragma unroll
;     for (int d = 0; d < DVB; ++d)
; #pragma unroll
;       for (int i = 0; i < 16; ++i) o[d][i] *= alpha;
;     m = mn;
;   }
; DI void kv_store(const KVRegs& R, bf16* Ks, bf16* Vs, int lane) {
; #pragma unroll
;   for (int i = 0; i < 4; ++i) { const int row = (lane >> 3) + 8 * i, ch = lane & 7; *(u32x4*)(Ks + row * WP + ch * 8) = R.k[i]; *(u32x4*)(Vs + row * WP + ch * 8) = R.v[i]; }
; }
; DI void band_load(KVRegs& R, const bf16* Kg, const bf16* Vg, int NP, int kstart, int dil, int roff, int lane) {
; #pragma unroll
;   for (int i = 0; i < 4; ++i) {
;     const int row = (lane >> 3) + 8 * i, ch = lane & 7; int k = kstart + row; if (k < 0) k = 0;
;     const size_t off = (size_t)(dil * k + roff) * NP + ch * 8;
;     R.k[i] = *(const u32x4*)(Kg + off); R.v[i] = *(const u32x4*)(Vg + off);
;   }
; }
; template <int DVB>
; DI void band_run(const bf16* Kg, const bf16* Vg, int NP, int kbase, int nsteps, int dil, int roff, int qidx, int win,
;                  const bf16x8 (&qf)[4], f32x16 (&o)[DVB], float& m, float& l, float c2, bf16* Ks, bf16* Vs, int lane) {
;   const int h = lane >> 5;
;   KVRegs R; band_load(R, Kg, Vg, NP, kbase, dil, roff, lane);
;   for (int j = 0; j < nsteps; ++j) {
;     lds_fence();
;     kv_store(R, Ks, Vs, lane);
;     lds_fence();
;     if (j + 1 < nsteps) band_load(R, Kg, Vg, NP, kbase + 32 * (j + 1), dil, roff, lane);
;     const int kb = kbase + 32 * j, lo_r = (qidx - win > 0 ? qidx - win : 0) - kb;
;     const unsigned vm = lane_rows(row_range_mask(lo_r, qidx - kb), h);
.LBB0_2635:
	v_max_i32_e32 v0, 0, v128
	v_lshlrev_b64 v[34:35], 13, v[0:1]
	v_or_b32_e32 v34, v34, v122
	v_max_i32_e32 v0, -8, v128
	s_waitcnt lgkmcnt(0)
	s_waitcnt vmcnt(7)
	ds_write_b128 v113, v[66:69]
	s_waitcnt vmcnt(6)
	ds_write_b128 v113, v[70:73] offset:4608
	s_waitcnt vmcnt(5)
	ds_write_b128 v113, v[74:77] offset:1152
	s_waitcnt vmcnt(4)
	ds_write_b128 v113, v[78:81] offset:5760
	s_waitcnt vmcnt(3)
	ds_write_b128 v113, v[82:85] offset:2304
	s_waitcnt vmcnt(2)
	ds_write_b128 v113, v[86:89] offset:6912
	s_waitcnt vmcnt(1)
	ds_write_b128 v113, v[94:97] offset:3456
	s_waitcnt vmcnt(0)
	ds_write_b128 v113, v[90:93] offset:8064
	v_lshl_add_u64 v[34:35], v[110:111], 0, v[34:35]
	v_add_u32_e32 v0, 8, v0
	s_waitcnt lgkmcnt(0)
	global_load_dwordx4 v[66:69], v[34:35], off offset:1024
	global_load_dwordx4 v[70:73], v[34:35], off offset:2048
	v_lshlrev_b64 v[34:35], 13, v[0:1]
	v_max_i32_e32 v0, -16, v128
	v_add_u32_e32 v0, 16, v0
	v_lshlrev_b64 v[38:39], 13, v[0:1]
	v_max_i32_e32 v0, 0xffffffe8, v128
	v_add_u32_e32 v0, 24, v0
	v_lshlrev_b64 v[90:91], 13, v[0:1]
	v_or_b32_e32 v34, v34, v122
	v_or_b32_e32 v38, v38, v122
	v_or_b32_e32 v90, v90, v122
	v_lshl_add_u64 v[34:35], v[110:111], 0, v[34:35]
	v_lshl_add_u64 v[38:39], v[110:111], 0, v[38:39]
	v_lshl_add_u64 v[90:91], v[110:111], 0, v[90:91]
	global_load_dwordx4 v[74:77], v[34:35], off offset:1024
	global_load_dwordx4 v[78:81], v[34:35], off offset:2048
	ds_read_b128 v[34:37], v114
	ds_read_b128 v[200:203], v114 offset:32
	ds_read_b128 v[204:207], v114 offset:64
	ds_read_b128 v[208:211], v114 offset:96
	global_load_dwordx4 v[82:85], v[38:39], off offset:1024
	global_load_dwordx4 v[86:89], v[38:39], off offset:2048
	global_load_dwordx4 v[94:97], v[90:91], off offset:1024
	s_nop 0
	global_load_dwordx4 v[90:93], v[90:91], off offset:2048
	s_waitcnt lgkmcnt(3)
	v_mfma_f32_32x32x16_bf16 v[34:49], v[34:37], v[62:65], 0
	v_add_u32_e32 v129, s15, v121
	v_min_i32_e32 v138, 31, v129
	v_add_u32_e32 v0, s15, v127
	v_max_i32_e32 v0, 0, v0
	v_cmp_gt_i32_e32 vcc, 31, v129
	s_waitcnt lgkmcnt(2)
	v_mfma_f32_32x32x16_bf16 v[34:49], v[200:203], v[58:61], v[34:49]
	v_add_u32_e32 v130, 1, v138
	v_lshlrev_b32_e64 v130, v130, -1
	v_not_b32_e32 v139, v130
	v_cndmask_b32_e32 v129, -1, v139, vcc
	v_cmp_ge_i32_e32 vcc, v138, v0
	s_waitcnt lgkmcnt(1)
	v_mfma_f32_32x32x16_bf16 v[34:49], v[204:207], v[54:57], v[34:49]
	v_lshlrev_b32_e64 v134, v0, -1
	v_and_b32_e32 v129, v129, v134
	v_cndmask_b32_e32 v0, 0, v129, vcc
	v_lshrrev_b32_e32 v134, v98, v0
	s_nop 0
	s_nop 0
	s_nop 0
	s_waitcnt lgkmcnt(0)
	v_mfma_f32_32x32x16_bf16 v[34:49], v[208:211], v[50:53], v[34:49]
	s_nop 11
	v_bfe_i32 v253, v134, 0, 1
	v_bfi_b32 v34, v253, v34, v123
	v_bfe_i32 v253, v134, 1, 1
	v_bfi_b32 v35, v253, v35, v123
	v_max3_f32 v130, v34, s2, v35
	v_bfe_i32 v253, v134, 2, 1
	v_bfi_b32 v129, v253, v36, v123
	v_bfe_i32 v253, v134, 3, 1
	v_bfi_b32 v0, v253, v37, v123
	v_max3_f32 v130, v130, v129, v0
	v_bfe_i32 v253, v134, 8, 1
	v_bfi_b32 v36, v253, v38, v123
	v_bfe_i32 v253, v134, 9, 1
	v_bfi_b32 v37, v253, v39, v123
	v_max3_f32 v130, v130, v36, v37
	v_bfe_i32 v253, v134, 10, 1
	v_bfi_b32 v38, v253, v40, v123
	v_bfe_i32 v253, v134, 11, 1
	v_bfi_b32 v39, v253, v41, v123
	v_max3_f32 v130, v130, v38, v39
	v_bfe_i32 v253, v134, 16, 1
	v_bfi_b32 v40, v253, v42, v123
	v_bfe_i32 v253, v134, 17, 1
	v_bfi_b32 v41, v253, v43, v123
	v_max3_f32 v130, v130, v40, v41
	v_bfe_i32 v253, v134, 18, 1
	v_bfi_b32 v42, v253, v44, v123
	v_bfe_i32 v253, v134, 19, 1
	v_bfi_b32 v43, v253, v45, v123
	v_max3_f32 v130, v130, v42, v43
	v_bfe_i32 v253, v134, 24, 1
	v_bfi_b32 v44, v253, v46, v123
	v_bfe_i32 v253, v134, 25, 1
	v_bfi_b32 v45, v253, v47, v123
	v_max3_f32 v130, v130, v44, v45
	v_bfe_i32 v253, v134, 26, 1
	v_bfi_b32 v46, v253, v48, v123
	s_nop 1
	v_bfe_i32 v253, v134, 27, 1
	v_bfi_b32 v47, v253, v49, v123
	v_max3_f32 v48, v130, v46, v47
	v_mov_b32_e32 v49, v48
	s_nop 1
	v_permlane32_swap_b32_e32 v48, v49
	v_max_f32_e32 v49, v49, v49
	v_max_f32_e32 v48, v48, v48
	v_max_f32_e32 v48, v48, v49
	v_mul_f32_e32 v48, 0x3e38aa3b, v48
	v_add_f32_e32 v49, 0x40c00000, v124
	v_cmp_gt_f32_e32 vcc, v48, v49
	s_cbranch_vccz .LBB0_2634
	v_max_f32_e32 v48, v48, v48
	v_max_f32_e32 v49, v124, v124
	v_max_f32_e32 v49, v49, v48
	v_sub_f32_e32 v48, v124, v49
	v_exp_f32_e32 v48, v48
	v_mov_b32_e32 v124, v49
	v_mul_f32_e32 v125, v125, v48
	v_pk_mul_f32 v[32:33], v[32:33], v[48:49] op_sel_hi:[1,0]
	v_pk_mul_f32 v[30:31], v[30:31], v[48:49] op_sel_hi:[1,0]
	v_pk_mul_f32 v[28:29], v[28:29], v[48:49] op_sel_hi:[1,0]
	v_pk_mul_f32 v[26:27], v[26:27], v[48:49] op_sel_hi:[1,0]
	v_pk_mul_f32 v[24:25], v[24:25], v[48:49] op_sel_hi:[1,0]
	v_pk_mul_f32 v[22:23], v[22:23], v[48:49] op_sel_hi:[1,0]
	v_pk_mul_f32 v[20:21], v[20:21], v[48:49] op_sel_hi:[1,0]
	v_pk_mul_f32 v[18:19], v[18:19], v[48:49] op_sel_hi:[1,0]
	v_pk_mul_f32 v[16:17], v[16:17], v[48:49] op_sel_hi:[1,0]
	v_pk_mul_f32 v[14:15], v[14:15], v[48:49] op_sel_hi:[1,0]
	v_pk_mul_f32 v[12:13], v[12:13], v[48:49] op_sel_hi:[1,0]
	v_pk_mul_f32 v[10:11], v[10:11], v[48:49] op_sel_hi:[1,0]
	v_pk_mul_f32 v[8:9], v[8:9], v[48:49] op_sel_hi:[1,0]
	v_pk_mul_f32 v[6:7], v[6:7], v[48:49] op_sel_hi:[1,0]
	v_pk_mul_f32 v[4:5], v[4:5], v[48:49] op_sel_hi:[1,0]
	v_pk_mul_f32 v[2:3], v[2:3], v[48:49] op_sel_hi:[1,0]
	s_branch .LBB0_2634
